# v90 + decode_pair key scores: 4 whole key rows per load instruction, DPP row sums, scores exchanged through the wave's LDS p buffer (f32 math, only the summation order inside a dot product differs)
# speedup vs baseline: 1.0308x; 1.0159x over previous
; #define LAS __attribute__((address_space(3)))
; DI void decode_pair(const Params& p, LAS float* L  , int pairidx, int wid, int lane) {
;     const int item = pairidx * 2 + (wid >> 2), kq = wid & 3;
;     const int b = item >> 4, h = item & 15;
;     const bf16_t* zrow = (const bf16_t*)(p.ws + WS_Z) + (size_t)(MP + b) * ZLD;
;     LAS float* wl = L + wid * 272; LAS float* qs = wl; LAS float* pb = wl + 64; LAS float* ob = wl + 192;
;     qs[lane] = bf2f(zrow[4096 + h * 64 + lane]) * 0.125f;
;     asm volatile("s_waitcnt lgkmcnt(0)" ::: "memory");
;     const float slope = exp2f(-0.5f * (float)(h + 1));
;     const float* ck = p.in[5]; const float* cv = p.in[6];
;     const float* knew = p.out + O_KS + b * 1024 + h * 64; const float* vnew = p.out + O_VS + b * 1024 + h * 64;
;     float sc[2]; float mx = -INFINITY;
; #pragma unroll
;     for (int i = 0; i < 2; ++i) {
;         const int e = kq + 4 * (lane + 64 * i);
;         sc[i] = -INFINITY;
;         if (e < 387) {
;             const int pi = e / 129, j = e - pi * 129, d = 1 << (2 * pi), idx = 2048 - j * d;
;             const float* kr = (idx == 2048) ? knew : ck + ((size_t)(b * 2048 + idx) * 16 + h) * 64;
;             float dot = 0.f;
; #pragma unroll
;             for (int dd = 0; dd < 64; dd += 4) { const f32x4 kv = __builtin_nontemporal_load((const f32x4*)(kr + dd)); const f32x4 qv = *(const LAS f32x4*)(qs + dd); dot += kv.x * qv.x + kv.y * qv.y + kv.z * qv.z + kv.w * qv.w; }
;             sc[i] = dot - slope * (float)(j * d);
;         }
.LBB0_302:
	v_lshl_add_u32 v0, s57, 1, v146
	v_and_b32_e32 v56, 15, v0
	v_ashrrev_i32_e32 v2, 4, v0
	v_lshlrev_b32_e32 v134, 6, v56
	v_add_u32_e32 v136, 0x4000, v2
	v_or_b32_e32 v0, v134, v129
	v_mad_i64_i32 v[138:139], s[0:1], v136, s48, v[132:133]
	v_lshlrev_b32_e32 v130, 1, v0
	v_lshl_add_u64 v[0:1], v[138:139], 0, v[130:131]
	v_add_co_u32_e32 v0, vcc, 0x2000, v0
	v_lshl_add_u32 v169, v2, 11, v167
	s_nop 0
	v_addc_co_u32_e32 v1, vcc, 0, v1, vcc
	global_load_ushort v3, v[0:1], off
	v_sub_u32_e32 v0, v169, v149
	v_lshlrev_b32_e32 v140, 10, v2
	v_ashrrev_i32_e32 v1, 31, v0
	v_ashrrev_i32_e32 v141, 31, v140
	v_lshlrev_b64 v[0:1], 12, v[0:1]
	v_lshl_add_u64 v[144:145], v[140:141], 2, s[40:41]
	v_lshl_add_u64 v[0:1], s[78:79], 0, v[0:1]
	v_lshlrev_b32_e32 v130, 8, v56
	v_cndmask_b32_e64 v1, v1, v145, s[8:9]
	v_cndmask_b32_e64 v0, v0, v144, s[8:9]
	v_lshl_add_u64 v[28:29], v[0:1], 0, v[130:131]
	v_add_u32_e32 v56, 1, v56
	v_cvt_f32_ubyte0_e32 v56, v56
	v_mul_f32_e32 v57, -0.5, v56
	v_cmp_gt_f32_e32 vcc, s49, v57
	v_lshlrev_b32_e32 v130, 2, v134
	s_waitcnt vmcnt(0)
	v_lshlrev_b32_e32 v0, 16, v3
	v_mul_f32_e32 v0, 0x3e000000, v0
	ds_write_b32 v148, v0
	s_waitcnt lgkmcnt(0)
	s_nop 0
	v_cndmask_b32_e32 v57, 0, v165, vcc
	v_fmac_f32_e32 v57, -0.5, v56
	v_exp_f32_e32 v56, v57
	v_cndmask_b32_e32 v57, 0, v166, vcc
	ds_read_b128 v[124:127], v147
	ds_read_b128 v[120:123], v147 offset:16
	ds_read_b128 v[96:99], v147 offset:96
	ds_read_b128 v[100:103], v147 offset:112
	ds_read_b128 v[116:119], v147 offset:32
	ds_read_b128 v[112:115], v147 offset:48
	ds_read_b128 v[108:111], v147 offset:64
	ds_read_b128 v[104:107], v147 offset:80
	ds_read_b128 v[88:91], v147 offset:128
	ds_read_b128 v[92:95], v147 offset:144
	v_ldexp_f32 v137, v56, v57
	ds_read_b128 v[76:79], v147 offset:160
	ds_read_b128 v[84:87], v147 offset:176
	ds_read_b128 v[60:63], v147 offset:192
	ds_read_b128 v[68:71], v147 offset:208
	ds_read_b128 v[56:59], v147 offset:224
	ds_read_b128 v[64:67], v147 offset:240
	s_waitcnt lgkmcnt(13)
	v_mov_b32_e32 v142, v99
	s_waitcnt lgkmcnt(12)
	v_mov_b32_e32 v143, v103
	v_mov_b32_e32 v99, v102
	v_mov_b32_e32 v102, v96
	v_mov_b32_e32 v103, v100
	v_mov_b32_e32 v100, v97
	s_waitcnt lgkmcnt(7)
	v_mov_b32_e32 v96, v91
	s_waitcnt lgkmcnt(6)
	v_mov_b32_e32 v97, v95
	v_mov_b32_e32 v91, v94
	v_mov_b32_e32 v94, v88
	v_mov_b32_e32 v95, v92
	v_mov_b32_e32 v92, v89
	s_waitcnt lgkmcnt(5)
	v_mov_b32_e32 v88, v79
	s_waitcnt lgkmcnt(4)
	v_mov_b32_e32 v89, v87
	v_mov_b32_e32 v79, v86
	v_mov_b32_e32 v86, v76
	v_mov_b32_e32 v87, v84
	v_mov_b32_e32 v84, v77
	s_waitcnt lgkmcnt(3)
	v_mov_b32_e32 v76, v63
	s_waitcnt lgkmcnt(2)
	v_mov_b32_e32 v77, v71
	v_mov_b32_e32 v63, v70
	v_mov_b32_e32 v70, v60
	v_mov_b32_e32 v71, v68
	v_mov_b32_e32 v68, v61
	s_waitcnt lgkmcnt(1)
	v_mov_b32_e32 v60, v59
	s_waitcnt lgkmcnt(0)
	v_mov_b32_e32 v61, v67
	v_mov_b32_e32 v59, v66
	v_mov_b32_e32 v66, v56
	v_mov_b32_e32 v67, v64
	v_mov_b32_e32 v64, v57
	v_mov_b32_e32 v56, 0xff800000
	s_and_saveexec_b64 s[0:1], s[10:11]
	s_cbranch_execz .LBB0_304
	v_sub_u32_e32 v56, v169, v151
	v_ashrrev_i32_e32 v57, 31, v56
	v_lshlrev_b64 v[56:57], 12, v[56:57]
	v_lshl_add_u64 v[56:57], s[78:79], 0, v[56:57]
	v_cndmask_b32_e64 v57, v57, v145, s[12:13]
	v_cndmask_b32_e64 v56, v56, v144, s[12:13]
	v_lshl_add_u64 v[56:57], v[56:57], 0, v[130:131]
	s_waitcnt vmcnt(15)
	v_mul_f32_e32 v176, v125, v171
	s_waitcnt vmcnt(14)
	v_mul_f32_e32 v240, v121, v179
	s_waitcnt vmcnt(13)
	v_mul_f32_e32 v241, v117, v183
	v_fmac_f32_e32 v176, v124, v170
	v_fmac_f32_e32 v240, v120, v178
	v_fmac_f32_e32 v241, v116, v182
	s_waitcnt vmcnt(9)
	v_mov_b32_e32 v56, v198
	s_waitcnt vmcnt(8)
	v_mov_b32_e32 v57, v202
	v_mov_b32_e32 v202, v199
	v_mov_b32_e32 v145, v204
	v_mov_b32_e32 v204, v201
	s_waitcnt vmcnt(6)
	v_mov_b32_e32 v175, v210
	v_mov_b32_e32 v210, v207
	s_waitcnt vmcnt(4)
	v_mov_b32_e32 v201, v218
	v_mov_b32_e32 v218, v215
	v_mov_b32_e32 v144, v200
	v_mov_b32_e32 v174, v206
	v_mov_b32_e32 v200, v214
	v_pk_mul_f32 v[170:171], v[100:101], v[202:203]
	v_pk_mul_f32 v[178:179], v[92:93], v[210:211]
	v_pk_mul_f32 v[182:183], v[84:85], v[218:219]
	v_fmac_f32_e32 v176, v126, v172
	v_mul_f32_e32 v242, v113, v187
	v_mov_b32_e32 v198, v208
	v_mov_b32_e32 v199, v212
	v_mov_b32_e32 v206, v216
	v_mov_b32_e32 v207, v220
	v_fmac_f32_e32 v240, v122, v180
	v_pk_fma_f32 v[56:57], v[102:103], v[56:57], v[170:171]
	v_pk_fma_f32 v[170:171], v[94:95], v[174:175], v[178:179]
	v_pk_fma_f32 v[174:175], v[86:87], v[200:201], v[182:183]
	v_fmac_f32_e32 v176, v127, v173
	v_mul_f32_e32 v191, v109, v191
	v_fmac_f32_e32 v242, v112, v186
	v_fmac_f32_e32 v241, v118, v184
	v_fmac_f32_e32 v240, v123, v181
	v_pk_fma_f32 v[56:57], v[98:99], v[144:145], v[56:57]
	v_pk_fma_f32 v[144:145], v[90:91], v[198:199], v[170:171]
	v_pk_fma_f32 v[170:171], v[78:79], v[206:207], v[174:175]
	v_add_f32_e32 v174, 0, v176
	v_mul_f32_e32 v195, v105, v195
	v_fmac_f32_e32 v191, v108, v190
	v_fmac_f32_e32 v242, v114, v188
	v_fmac_f32_e32 v241, v119, v185
	v_add_f32_e32 v174, v174, v240
	v_fmac_f32_e32 v195, v104, v194
	v_fmac_f32_e32 v191, v110, v192
	v_fmac_f32_e32 v242, v115, v189
	v_add_f32_e32 v174, v174, v241
	v_fmac_f32_e32 v195, v106, v196
	v_fmac_f32_e32 v191, v111, v193
	v_add_f32_e32 v174, v174, v242
	v_fmac_f32_e32 v195, v107, v197
	v_add_f32_e32 v174, v174, v191
	v_pk_fma_f32 v[56:57], v[142:143], v[204:205], v[56:57]
	v_add_f32_e32 v174, v174, v195
	v_mov_b32_e32 v212, v209
	v_add_f32_e32 v56, v174, v56
	s_waitcnt vmcnt(2)
	v_mov_b32_e32 v209, v228
	v_mov_b32_e32 v228, v223
	v_pk_fma_f32 v[144:145], v[96:97], v[212:213], v[144:145]
	v_add_f32_e32 v56, v56, v57
	v_mov_b32_e32 v220, v217
	v_mov_b32_e32 v208, v222
	v_pk_mul_f32 v[186:187], v[68:69], v[228:229]
	v_add_f32_e32 v56, v56, v144
	v_mov_b32_e32 v214, v224
	v_mov_b32_e32 v215, v230
	v_pk_fma_f32 v[178:179], v[70:71], v[208:209], v[186:187]
	v_pk_fma_f32 v[170:171], v[88:89], v[220:221], v[170:171]
	v_add_f32_e32 v56, v56, v145
	v_mov_b32_e32 v230, v225
	v_pk_fma_f32 v[172:173], v[62:63], v[214:215], v[178:179]
	v_add_f32_e32 v56, v56, v170
	v_pk_fma_f32 v[172:173], v[76:77], v[230:231], v[172:173]
	v_add_f32_e32 v56, v56, v171
	s_waitcnt vmcnt(0)
	v_mov_b32_e32 v217, v236
	v_mov_b32_e32 v236, v233
	v_add_f32_e32 v56, v56, v172
	v_mov_b32_e32 v216, v232
	v_add_f32_e32 v170, v56, v173
	v_pk_mul_f32 v[56:57], v[64:65], v[236:237]
	v_mov_b32_e32 v144, v234
	v_pk_fma_f32 v[56:57], v[66:67], v[216:217], v[56:57]
	v_mov_b32_e32 v145, v238
	v_pk_fma_f32 v[56:57], v[58:59], v[144:145], v[56:57]
	v_mov_b32_e32 v238, v235
	v_pk_fma_f32 v[56:57], v[60:61], v[238:239], v[56:57]
	s_nop 0
	v_add_f32_e32 v56, v170, v56
	v_add_f32_e32 v56, v56, v57
	v_fma_f32 v56, -v137, v152, v56
; #define LAS __attribute__((address_space(3)))
; DI void decode_pair(const Params& p, LAS float* L  , int pairidx, int wid, int lane) {
;     ...
;     for (int i = 0; i < 2; ++i) {
;         const int e = kq + 4 * (lane + 64 * i);
;         sc[i] = -INFINITY;
;         if (e < 387) {
;             const int pi = e / 129, j = e - pi * 129, d = 1 << (2 * pi), idx = 2048 - j * d;
;             const float* kr = (idx == 2048) ? knew : ck + ((size_t)(b * 2048 + idx) * 16 + h) * 64;
;             float dot = 0.f;
; #pragma unroll
;             for (int dd = 0; dd < 64; dd += 4) { const f32x4 kv = __builtin_nontemporal_load((const f32x4*)(kr + dd)); const f32x4 qv = *(const LAS f32x4*)(qs + dd); dot += kv.x * qv.x + kv.y * qv.y + kv.z * qv.z + kv.w * qv.w; }
;             sc[i] = dot - slope * (float)(j * d);
;         }
.LBB0_304:
	s_or_b64 exec, exec, s[0:1]
	s_waitcnt vmcnt(12)
	v_mul_f32_e32 v57, v81, v125
	v_fmac_f32_e32 v57, v80, v124
	v_mul_f32_e32 v73, v73, v121
	v_fmac_f32_e32 v57, v82, v126
	v_fmac_f32_e32 v73, v72, v120
	v_mul_f32_e32 v53, v53, v117
	v_fmac_f32_e32 v57, v83, v127
	v_fmac_f32_e32 v73, v74, v122
	v_fmac_f32_e32 v53, v52, v116
	v_mul_f32_e32 v45, v45, v113
	v_add_f32_e32 v57, 0, v57
	v_fmac_f32_e32 v73, v75, v123
	v_fmac_f32_e32 v53, v54, v118
	v_fmac_f32_e32 v45, v44, v112
	v_add_f32_e32 v57, v57, v73
	v_fmac_f32_e32 v53, v55, v119
	v_fmac_f32_e32 v45, v46, v114
	v_add_f32_e32 v52, v57, v53
	v_fmac_f32_e32 v45, v47, v115
	v_add_f32_e32 v44, v52, v45
	s_waitcnt vmcnt(8)
	v_mul_f32_e32 v45, v49, v109
	v_fmac_f32_e32 v45, v48, v108
	v_mul_f32_e32 v41, v41, v105
	v_fmac_f32_e32 v45, v50, v110
	v_fmac_f32_e32 v41, v40, v104
	v_fmac_f32_e32 v45, v51, v111
	v_fmac_f32_e32 v41, v42, v106
	v_add_f32_e32 v44, v44, v45
	v_fmac_f32_e32 v41, v43, v107
	v_add_f32_e32 v42, v44, v41
	v_mov_b32_e32 v41, v27
	v_mov_b32_e32 v27, v24
	v_mov_b32_e32 v24, v17
	v_mov_b32_e32 v40, v19
	v_mov_b32_e32 v19, v26
	v_mov_b32_e32 v26, v16
	v_pk_mul_f32 v[16:17], v[24:25], v[100:101]
	s_nop 0
	v_pk_fma_f32 v[16:17], v[26:27], v[102:103], v[16:17]
	s_nop 0
	v_pk_fma_f32 v[16:17], v[18:19], v[98:99], v[16:17]
	s_waitcnt vmcnt(4)
	v_mov_b32_e32 v19, v36
	v_pk_fma_f32 v[16:17], v[40:41], v[142:143], v[16:17]
	v_mov_b32_e32 v36, v33
	v_add_f32_e32 v16, v42, v16
	v_mov_b32_e32 v18, v32
	v_pk_mul_f32 v[24:25], v[36:37], v[92:93]
	v_add_f32_e32 v26, v16, v17
	v_mov_b32_e32 v16, v35
	v_mov_b32_e32 v35, v38
	v_pk_fma_f32 v[18:19], v[18:19], v[94:95], v[24:25]
	v_mov_b32_e32 v17, v39
	v_pk_fma_f32 v[18:19], v[34:35], v[90:91], v[18:19]
	s_nop 0
	v_pk_fma_f32 v[16:17], v[16:17], v[96:97], v[18:19]
	s_nop 0
	v_add_f32_e32 v16, v26, v16
	v_add_f32_e32 v18, v16, v17
	v_mov_b32_e32 v17, v15
	v_mov_b32_e32 v15, v12
	v_mov_b32_e32 v12, v9
	v_mov_b32_e32 v16, v11
	v_mov_b32_e32 v11, v14
	v_mov_b32_e32 v14, v8
	v_pk_mul_f32 v[8:9], v[12:13], v[84:85]
	s_nop 0
	v_pk_fma_f32 v[8:9], v[14:15], v[86:87], v[8:9]
	s_nop 0
	v_pk_fma_f32 v[8:9], v[10:11], v[78:79], v[8:9]
	s_waitcnt vmcnt(0)
	v_mov_b32_e32 v11, v28
	v_pk_fma_f32 v[8:9], v[16:17], v[88:89], v[8:9]
	v_mov_b32_e32 v28, v21
	v_add_f32_e32 v8, v18, v8
	v_mov_b32_e32 v10, v20
	v_pk_mul_f32 v[12:13], v[28:29], v[68:69]
	v_add_f32_e32 v14, v8, v9
	v_mov_b32_e32 v8, v23
	v_mov_b32_e32 v23, v30
	v_pk_fma_f32 v[10:11], v[10:11], v[70:71], v[12:13]
	v_mov_b32_e32 v9, v31
	v_pk_fma_f32 v[10:11], v[22:23], v[62:63], v[10:11]
	v_mov_b32_e32 v13, v155
	v_pk_fma_f32 v[8:9], v[8:9], v[76:77], v[10:11]
	s_nop 0
	v_add_f32_e32 v8, v14, v8
	v_add_f32_e32 v10, v8, v9
	v_mov_b32_e32 v9, v7
	v_mov_b32_e32 v7, v4
	v_mov_b32_e32 v4, v1
	v_mov_b32_e32 v8, v3
	v_mov_b32_e32 v3, v6
	v_mov_b32_e32 v6, v0
	v_pk_mul_f32 v[0:1], v[4:5], v[64:65]
	s_nop 0
	v_pk_fma_f32 v[0:1], v[6:7], v[66:67], v[0:1]
	s_nop 0
	v_pk_fma_f32 v[0:1], v[2:3], v[58:59], v[0:1]
	v_xor_b32_e32 v3, 1, v168
	v_pk_fma_f32 v[0:1], v[8:9], v[60:61], v[0:1]
	s_nop 0
	v_add_f32_e32 v0, v10, v0
	v_add_f32_e32 v0, v0, v1
	v_and_b32_e32 v1, 64, v168
	v_add_u32_e32 v1, 64, v1
	v_cmp_lt_i32_e32 vcc, v3, v1
	v_fma_f32 v2, -v137, v150, v0
	s_mov_b64 s[96:97], vcc
	v_lshrrev_b32_e32 v126, 6, v226
	v_and_b32_e32 v174, 3, v126
	v_lshrrev_b32_e32 v126, 2, v126
	v_lshl_add_u32 v126, s57, 1, v126
	v_and_b32_e32 v127, 15, v126
	v_lshrrev_b32_e32 v126, 4, v126
	v_lshrrev_b32_e32 v170, 4, v168
	v_and_b32_e32 v172, 15, v168
	v_lshlrev_b32_e32 v180, 8, v127
	v_lshl_add_u32 v180, v172, 4, v180
	v_lshl_add_u32 v178, v126, 11, 0
	v_add_u32_e32 v178, 0x800, v178
	v_add_u32_e32 v142, 1, v174
	v_lshrrev_b32_e32 v142, 2, v142
	v_sub_u32_e32 v176, 96, v142
	v_add_u32_e32 v142, 1, v127
	v_cvt_f32_u32_e32 v142, v142
	v_mul_f32_e32 v142, -0.5, v142
	v_exp_f32_e32 v182, v142
	v_lshl_add_u32 v142, v172, 4, v147
	ds_read_b128 v[220:223], v142
	v_lshl_add_u32 v184, v170, 2, v147
	v_add_u32_e32 v184, 0x100, v184
	v_lshl_add_u32 v186, v168, 2, v147
	v_add_u32_e32 v186, 0x100, v186
	v_lshl_add_u32 v143, v126, 12, v180
	s_nop 0
	v_readfirstlane_b32 s32, v174
	v_add_u32_e32 v126, 0, v170
	v_min_u32_e32 v126, v126, v176
	v_lshl_add_u32 v126, v126, 2, v174
	v_mul_u32_u24_e32 v127, 0x1fd, v126
	v_lshrrev_b32_e32 v127, 16, v127
	v_mul_u32_u24_e32 v142, 0x81, v127
	v_sub_u32_e32 v126, v126, v142
	v_lshlrev_b32_e32 v127, 1, v127
	v_lshlrev_b32_e32 v126, v127, v126
	v_cvt_f32_u32_e32 v228, v126
	v_max_u32_e32 v126, 1, v126
	v_sub_u32_e32 v126, v178, v126
	v_lshl_add_u32 v126, v126, 12, v180
	global_load_dwordx4 v[4:7], v126, s[78:79] nt
	v_mul_f32_e32 v228, v182, v228
	v_add_u32_e32 v126, 4, v170
	v_min_u32_e32 v126, v126, v176
	v_lshl_add_u32 v126, v126, 2, v174
	v_mul_u32_u24_e32 v127, 0x1fd, v126
	v_lshrrev_b32_e32 v127, 16, v127
	v_mul_u32_u24_e32 v142, 0x81, v127
	v_sub_u32_e32 v126, v126, v142
	v_lshlrev_b32_e32 v127, 1, v127
	v_lshlrev_b32_e32 v126, v127, v126
	v_cvt_f32_u32_e32 v229, v126
	v_max_u32_e32 v126, 1, v126
	v_sub_u32_e32 v126, v178, v126
	v_lshl_add_u32 v126, v126, 12, v180
	global_load_dwordx4 v[8:11], v126, s[78:79] nt
	v_mul_f32_e32 v229, v182, v229
	v_add_u32_e32 v126, 8, v170
	v_min_u32_e32 v126, v126, v176
	v_lshl_add_u32 v126, v126, 2, v174
	v_mul_u32_u24_e32 v127, 0x1fd, v126
	v_lshrrev_b32_e32 v127, 16, v127
	v_mul_u32_u24_e32 v142, 0x81, v127
	v_sub_u32_e32 v126, v126, v142
	v_lshlrev_b32_e32 v127, 1, v127
	v_lshlrev_b32_e32 v126, v127, v126
	v_cvt_f32_u32_e32 v230, v126
	v_max_u32_e32 v126, 1, v126
	v_sub_u32_e32 v126, v178, v126
	v_lshl_add_u32 v126, v126, 12, v180
	global_load_dwordx4 v[12:15], v126, s[78:79] nt
; #define LAS __attribute__((address_space(3)))
; DI void decode_pair(const Params& p, LAS float* L  , int pairidx, int wid, int lane) {
;     ...
;     for (int i = 0; i < 2; ++i) {
;         const int e = kq + 4 * (lane + 64 * i);
;         sc[i] = -INFINITY;
;         if (e < 387) {
;             const int pi = e / 129, j = e - pi * 129, d = 1 << (2 * pi), idx = 2048 - j * d;
;             const float* kr = (idx == 2048) ? knew : ck + ((size_t)(b * 2048 + idx) * 16 + h) * 64;
;             float dot = 0.f;
; #pragma unroll
;             for (int dd = 0; dd < 64; dd += 4) { const f32x4 kv = __builtin_nontemporal_load((const f32x4*)(kr + dd)); const f32x4 qv = *(const LAS f32x4*)(qs + dd); dot += kv.x * qv.x + kv.y * qv.y + kv.z * qv.z + kv.w * qv.w; }
;             sc[i] = dot - slope * (float)(j * d);
	v_mul_f32_e32 v230, v182, v230
	v_add_u32_e32 v126, 12, v170
	v_min_u32_e32 v126, v126, v176
	v_lshl_add_u32 v126, v126, 2, v174
	v_mul_u32_u24_e32 v127, 0x1fd, v126
	v_lshrrev_b32_e32 v127, 16, v127
	v_mul_u32_u24_e32 v142, 0x81, v127
	v_sub_u32_e32 v126, v126, v142
	v_lshlrev_b32_e32 v127, 1, v127
	v_lshlrev_b32_e32 v126, v127, v126
	v_cvt_f32_u32_e32 v231, v126
	v_max_u32_e32 v126, 1, v126
	v_sub_u32_e32 v126, v178, v126
	v_lshl_add_u32 v126, v126, 12, v180
	global_load_dwordx4 v[16:19], v126, s[78:79] nt
	v_mul_f32_e32 v231, v182, v231
	v_add_u32_e32 v126, 16, v170
	v_min_u32_e32 v126, v126, v176
	v_lshl_add_u32 v126, v126, 2, v174
	v_mul_u32_u24_e32 v127, 0x1fd, v126
	v_lshrrev_b32_e32 v127, 16, v127
	v_mul_u32_u24_e32 v142, 0x81, v127
	v_sub_u32_e32 v126, v126, v142
	v_lshlrev_b32_e32 v127, 1, v127
	v_lshlrev_b32_e32 v126, v127, v126
	v_cvt_f32_u32_e32 v232, v126
	v_max_u32_e32 v126, 1, v126
	v_sub_u32_e32 v126, v178, v126
	v_lshl_add_u32 v126, v126, 12, v180
	global_load_dwordx4 v[20:23], v126, s[78:79] nt
	v_mul_f32_e32 v232, v182, v232
	v_add_u32_e32 v126, 20, v170
	v_min_u32_e32 v126, v126, v176
	v_lshl_add_u32 v126, v126, 2, v174
	v_mul_u32_u24_e32 v127, 0x1fd, v126
	v_lshrrev_b32_e32 v127, 16, v127
	v_mul_u32_u24_e32 v142, 0x81, v127
	v_sub_u32_e32 v126, v126, v142
	v_lshlrev_b32_e32 v127, 1, v127
	v_lshlrev_b32_e32 v126, v127, v126
	v_cvt_f32_u32_e32 v233, v126
	v_max_u32_e32 v126, 1, v126
	v_sub_u32_e32 v126, v178, v126
	v_lshl_add_u32 v126, v126, 12, v180
	global_load_dwordx4 v[24:27], v126, s[78:79] nt
	v_mul_f32_e32 v233, v182, v233
	v_add_u32_e32 v126, 24, v170
	v_min_u32_e32 v126, v126, v176
	v_lshl_add_u32 v126, v126, 2, v174
	v_mul_u32_u24_e32 v127, 0x1fd, v126
	v_lshrrev_b32_e32 v127, 16, v127
	v_mul_u32_u24_e32 v142, 0x81, v127
	v_sub_u32_e32 v126, v126, v142
	v_lshlrev_b32_e32 v127, 1, v127
	v_lshlrev_b32_e32 v126, v127, v126
	v_cvt_f32_u32_e32 v234, v126
	v_max_u32_e32 v126, 1, v126
	v_sub_u32_e32 v126, v178, v126
	v_lshl_add_u32 v126, v126, 12, v180
	global_load_dwordx4 v[28:31], v126, s[78:79] nt
	v_mul_f32_e32 v234, v182, v234
	v_add_u32_e32 v126, 28, v170
	v_min_u32_e32 v126, v126, v176
	v_lshl_add_u32 v126, v126, 2, v174
	v_mul_u32_u24_e32 v127, 0x1fd, v126
	v_lshrrev_b32_e32 v127, 16, v127
	v_mul_u32_u24_e32 v142, 0x81, v127
	v_sub_u32_e32 v126, v126, v142
	v_lshlrev_b32_e32 v127, 1, v127
	v_lshlrev_b32_e32 v126, v127, v126
	v_cvt_f32_u32_e32 v235, v126
	v_max_u32_e32 v126, 1, v126
	v_sub_u32_e32 v126, v178, v126
	v_lshl_add_u32 v126, v126, 12, v180
	global_load_dwordx4 v[32:35], v126, s[78:79] nt
	v_mul_f32_e32 v235, v182, v235
	v_add_u32_e32 v126, 32, v170
	v_min_u32_e32 v126, v126, v176
	v_lshl_add_u32 v126, v126, 2, v174
	v_mul_u32_u24_e32 v127, 0x1fd, v126
	v_lshrrev_b32_e32 v127, 16, v127
	v_mul_u32_u24_e32 v142, 0x81, v127
	v_sub_u32_e32 v126, v126, v142
	v_lshlrev_b32_e32 v127, 1, v127
	v_lshlrev_b32_e32 v126, v127, v126
	v_cvt_f32_u32_e32 v236, v126
	v_max_u32_e32 v126, 1, v126
	v_sub_u32_e32 v126, v178, v126
	v_lshl_add_u32 v126, v126, 12, v180
	global_load_dwordx4 v[36:39], v126, s[78:79] nt
	v_mul_f32_e32 v236, v182, v236
	v_add_u32_e32 v126, 36, v170
	v_min_u32_e32 v126, v126, v176
	v_lshl_add_u32 v126, v126, 2, v174
	v_mul_u32_u24_e32 v127, 0x1fd, v126
	v_lshrrev_b32_e32 v127, 16, v127
	v_mul_u32_u24_e32 v142, 0x81, v127
	v_sub_u32_e32 v126, v126, v142
	v_lshlrev_b32_e32 v127, 1, v127
	v_lshlrev_b32_e32 v126, v127, v126
	v_cvt_f32_u32_e32 v237, v126
	v_max_u32_e32 v126, 1, v126
	v_sub_u32_e32 v126, v178, v126
	v_lshl_add_u32 v126, v126, 12, v180
	global_load_dwordx4 v[40:43], v126, s[78:79] nt
	v_mul_f32_e32 v237, v182, v237
	v_add_u32_e32 v126, 40, v170
	v_min_u32_e32 v126, v126, v176
	v_lshl_add_u32 v126, v126, 2, v174
	v_mul_u32_u24_e32 v127, 0x1fd, v126
	v_lshrrev_b32_e32 v127, 16, v127
	v_mul_u32_u24_e32 v142, 0x81, v127
	v_sub_u32_e32 v126, v126, v142
	v_lshlrev_b32_e32 v127, 1, v127
	v_lshlrev_b32_e32 v126, v127, v126
	v_cvt_f32_u32_e32 v238, v126
	v_max_u32_e32 v126, 1, v126
	v_sub_u32_e32 v126, v178, v126
	v_lshl_add_u32 v126, v126, 12, v180
	global_load_dwordx4 v[44:47], v126, s[78:79] nt
	v_mul_f32_e32 v238, v182, v238
	v_add_u32_e32 v126, 44, v170
	v_min_u32_e32 v126, v126, v176
	v_lshl_add_u32 v126, v126, 2, v174
	v_mul_u32_u24_e32 v127, 0x1fd, v126
	v_lshrrev_b32_e32 v127, 16, v127
	v_mul_u32_u24_e32 v142, 0x81, v127
	v_sub_u32_e32 v126, v126, v142
	v_lshlrev_b32_e32 v127, 1, v127
	v_lshlrev_b32_e32 v126, v127, v126
	v_cvt_f32_u32_e32 v239, v126
	v_max_u32_e32 v126, 1, v126
	v_sub_u32_e32 v126, v178, v126
	v_lshl_add_u32 v126, v126, 12, v180
	global_load_dwordx4 v[48:51], v126, s[78:79] nt
	v_mul_f32_e32 v239, v182, v239
	v_add_u32_e32 v126, 48, v170
	v_min_u32_e32 v126, v126, v176
	v_lshl_add_u32 v126, v126, 2, v174
	v_mul_u32_u24_e32 v127, 0x1fd, v126
	v_lshrrev_b32_e32 v127, 16, v127
	v_mul_u32_u24_e32 v142, 0x81, v127
	v_sub_u32_e32 v126, v126, v142
	v_lshlrev_b32_e32 v127, 1, v127
	v_lshlrev_b32_e32 v126, v127, v126
	v_cvt_f32_u32_e32 v240, v126
	v_max_u32_e32 v126, 1, v126
	v_sub_u32_e32 v126, v178, v126
	v_lshl_add_u32 v126, v126, 12, v180
	global_load_dwordx4 v[52:55], v126, s[78:79] nt
	v_mul_f32_e32 v240, v182, v240
	v_add_u32_e32 v126, 52, v170
	v_min_u32_e32 v126, v126, v176
	v_lshl_add_u32 v126, v126, 2, v174
	v_mul_u32_u24_e32 v127, 0x1fd, v126
	v_lshrrev_b32_e32 v127, 16, v127
	v_mul_u32_u24_e32 v142, 0x81, v127
	v_sub_u32_e32 v126, v126, v142
	v_lshlrev_b32_e32 v127, 1, v127
	v_lshlrev_b32_e32 v126, v127, v126
	v_cvt_f32_u32_e32 v241, v126
	v_max_u32_e32 v126, 1, v126
	v_sub_u32_e32 v126, v178, v126
	v_lshl_add_u32 v126, v126, 12, v180
; #define LAS __attribute__((address_space(3)))
; DI void decode_pair(const Params& p, LAS float* L  , int pairidx, int wid, int lane) {
;     ...
;     for (int i = 0; i < 2; ++i) {
;         const int e = kq + 4 * (lane + 64 * i);
;         sc[i] = -INFINITY;
;         if (e < 387) {
;             const int pi = e / 129, j = e - pi * 129, d = 1 << (2 * pi), idx = 2048 - j * d;
;             const float* kr = (idx == 2048) ? knew : ck + ((size_t)(b * 2048 + idx) * 16 + h) * 64;
;             float dot = 0.f;
; #pragma unroll
;             for (int dd = 0; dd < 64; dd += 4) { const f32x4 kv = __builtin_nontemporal_load((const f32x4*)(kr + dd)); const f32x4 qv = *(const LAS f32x4*)(qs + dd); dot += kv.x * qv.x + kv.y * qv.y + kv.z * qv.z + kv.w * qv.w; }
;             sc[i] = dot - slope * (float)(j * d);
	global_load_dwordx4 v[60:63], v126, s[78:79] nt
	v_mul_f32_e32 v241, v182, v241
	v_add_u32_e32 v126, 56, v170
	v_min_u32_e32 v126, v126, v176
	v_lshl_add_u32 v126, v126, 2, v174
	v_mul_u32_u24_e32 v127, 0x1fd, v126
	v_lshrrev_b32_e32 v127, 16, v127
	v_mul_u32_u24_e32 v142, 0x81, v127
	v_sub_u32_e32 v126, v126, v142
	v_lshlrev_b32_e32 v127, 1, v127
	v_lshlrev_b32_e32 v126, v127, v126
	v_cvt_f32_u32_e32 v242, v126
	v_max_u32_e32 v126, 1, v126
	v_sub_u32_e32 v126, v178, v126
	v_lshl_add_u32 v126, v126, 12, v180
	global_load_dwordx4 v[64:67], v126, s[78:79] nt
	v_mul_f32_e32 v242, v182, v242
	v_add_u32_e32 v126, 60, v170
	v_min_u32_e32 v126, v126, v176
	v_lshl_add_u32 v126, v126, 2, v174
	v_mul_u32_u24_e32 v127, 0x1fd, v126
	v_lshrrev_b32_e32 v127, 16, v127
	v_mul_u32_u24_e32 v142, 0x81, v127
	v_sub_u32_e32 v126, v126, v142
	v_lshlrev_b32_e32 v127, 1, v127
	v_lshlrev_b32_e32 v126, v127, v126
	v_cvt_f32_u32_e32 v124, v126
	v_max_u32_e32 v126, 1, v126
	v_sub_u32_e32 v126, v178, v126
	v_lshl_add_u32 v126, v126, 12, v180
	global_load_dwordx4 v[68:71], v126, s[78:79] nt
	v_mul_f32_e32 v124, v182, v124
	v_add_u32_e32 v126, 64, v170
	v_min_u32_e32 v126, v126, v176
	v_lshl_add_u32 v126, v126, 2, v174
	v_mul_u32_u24_e32 v127, 0x1fd, v126
	v_lshrrev_b32_e32 v127, 16, v127
	v_mul_u32_u24_e32 v142, 0x81, v127
	v_sub_u32_e32 v126, v126, v142
	v_lshlrev_b32_e32 v127, 1, v127
	v_lshlrev_b32_e32 v126, v127, v126
	v_cvt_f32_u32_e32 v125, v126
	v_max_u32_e32 v126, 1, v126
	v_sub_u32_e32 v126, v178, v126
	v_lshl_add_u32 v126, v126, 12, v180
	global_load_dwordx4 v[72:75], v126, s[78:79] nt
	v_mul_f32_e32 v125, v182, v125
	v_add_u32_e32 v126, 68, v170
	v_min_u32_e32 v126, v126, v176
	v_lshl_add_u32 v126, v126, 2, v174
	v_mul_u32_u24_e32 v127, 0x1fd, v126
	v_lshrrev_b32_e32 v127, 16, v127
	v_mul_u32_u24_e32 v142, 0x81, v127
	v_sub_u32_e32 v126, v126, v142
	v_lshlrev_b32_e32 v127, 1, v127
	v_lshlrev_b32_e32 v126, v127, v126
	v_cvt_f32_u32_e32 v188, v126
	v_max_u32_e32 v126, 1, v126
	v_sub_u32_e32 v126, v178, v126
	v_lshl_add_u32 v126, v126, 12, v180
	global_load_dwordx4 v[76:79], v126, s[78:79] nt
	v_mul_f32_e32 v188, v182, v188
	v_add_u32_e32 v126, 72, v170
	v_min_u32_e32 v126, v126, v176
	v_lshl_add_u32 v126, v126, 2, v174
	v_mul_u32_u24_e32 v127, 0x1fd, v126
	v_lshrrev_b32_e32 v127, 16, v127
	v_mul_u32_u24_e32 v142, 0x81, v127
	v_sub_u32_e32 v126, v126, v142
	v_lshlrev_b32_e32 v127, 1, v127
	v_lshlrev_b32_e32 v126, v127, v126
	v_cvt_f32_u32_e32 v190, v126
	v_max_u32_e32 v126, 1, v126
	v_sub_u32_e32 v126, v178, v126
	v_lshl_add_u32 v126, v126, 12, v180
	global_load_dwordx4 v[80:83], v126, s[78:79] nt
	v_mul_f32_e32 v190, v182, v190
	v_add_u32_e32 v126, 76, v170
	v_min_u32_e32 v126, v126, v176
	v_lshl_add_u32 v126, v126, 2, v174
	v_mul_u32_u24_e32 v127, 0x1fd, v126
	v_lshrrev_b32_e32 v127, 16, v127
	v_mul_u32_u24_e32 v142, 0x81, v127
	v_sub_u32_e32 v126, v126, v142
	v_lshlrev_b32_e32 v127, 1, v127
	v_lshlrev_b32_e32 v126, v127, v126
	v_cvt_f32_u32_e32 v192, v126
	v_max_u32_e32 v126, 1, v126
	v_sub_u32_e32 v126, v178, v126
	v_lshl_add_u32 v126, v126, 12, v180
	global_load_dwordx4 v[84:87], v126, s[78:79] nt
	v_mul_f32_e32 v192, v182, v192
	v_add_u32_e32 v126, 80, v170
	v_min_u32_e32 v126, v126, v176
	v_lshl_add_u32 v126, v126, 2, v174
	v_mul_u32_u24_e32 v127, 0x1fd, v126
	v_lshrrev_b32_e32 v127, 16, v127
	v_mul_u32_u24_e32 v142, 0x81, v127
	v_sub_u32_e32 v126, v126, v142
	v_lshlrev_b32_e32 v127, 1, v127
	v_lshlrev_b32_e32 v126, v127, v126
	v_cvt_f32_u32_e32 v194, v126
	v_max_u32_e32 v126, 1, v126
	v_sub_u32_e32 v126, v178, v126
	v_lshl_add_u32 v126, v126, 12, v180
	global_load_dwordx4 v[88:91], v126, s[78:79] nt
	v_mul_f32_e32 v194, v182, v194
	v_add_u32_e32 v126, 84, v170
	v_min_u32_e32 v126, v126, v176
	v_lshl_add_u32 v126, v126, 2, v174
	v_mul_u32_u24_e32 v127, 0x1fd, v126
	v_lshrrev_b32_e32 v127, 16, v127
	v_mul_u32_u24_e32 v142, 0x81, v127
	v_sub_u32_e32 v126, v126, v142
	v_lshlrev_b32_e32 v127, 1, v127
	v_lshlrev_b32_e32 v126, v127, v126
	v_cvt_f32_u32_e32 v196, v126
	v_max_u32_e32 v126, 1, v126
	v_sub_u32_e32 v126, v178, v126
	v_lshl_add_u32 v126, v126, 12, v180
	global_load_dwordx4 v[92:95], v126, s[78:79] nt
	v_mul_f32_e32 v196, v182, v196
	v_add_u32_e32 v126, 88, v170
	v_min_u32_e32 v126, v126, v176
	v_lshl_add_u32 v126, v126, 2, v174
	v_mul_u32_u24_e32 v127, 0x1fd, v126
	v_lshrrev_b32_e32 v127, 16, v127
	v_mul_u32_u24_e32 v142, 0x81, v127
	v_sub_u32_e32 v126, v126, v142
	v_lshlrev_b32_e32 v127, 1, v127
	v_lshlrev_b32_e32 v126, v127, v126
	v_cvt_f32_u32_e32 v198, v126
	v_max_u32_e32 v126, 1, v126
	v_sub_u32_e32 v126, v178, v126
	v_lshl_add_u32 v126, v126, 12, v180
	global_load_dwordx4 v[96:99], v126, s[78:79] nt
	v_mul_f32_e32 v198, v182, v198
	v_add_u32_e32 v126, 92, v170
	v_min_u32_e32 v126, v126, v176
	v_lshl_add_u32 v126, v126, 2, v174
	v_mul_u32_u24_e32 v127, 0x1fd, v126
	v_lshrrev_b32_e32 v127, 16, v127
	v_mul_u32_u24_e32 v142, 0x81, v127
	v_sub_u32_e32 v126, v126, v142
	v_lshlrev_b32_e32 v127, 1, v127
	v_lshlrev_b32_e32 v126, v127, v126
	v_cvt_f32_u32_e32 v200, v126
	v_max_u32_e32 v126, 1, v126
	v_sub_u32_e32 v126, v178, v126
	v_lshl_add_u32 v126, v126, 12, v180
	global_load_dwordx4 v[100:103], v126, s[78:79] nt
	v_mul_f32_e32 v200, v182, v200
	v_add_u32_e32 v126, 96, v170
	v_min_u32_e32 v126, v126, v176
	v_lshl_add_u32 v126, v126, 2, v174
	v_mul_u32_u24_e32 v127, 0x1fd, v126
	v_lshrrev_b32_e32 v127, 16, v127
	v_mul_u32_u24_e32 v142, 0x81, v127
	v_sub_u32_e32 v126, v126, v142
	v_lshlrev_b32_e32 v127, 1, v127
	v_lshlrev_b32_e32 v126, v127, v126
	v_cvt_f32_u32_e32 v202, v126
	v_max_u32_e32 v126, 1, v126
	v_sub_u32_e32 v126, v178, v126
	v_lshl_add_u32 v126, v126, 12, v180
	global_load_dwordx4 v[104:107], v126, s[78:79] nt
	v_mul_f32_e32 v202, v182, v202
	s_mov_b64 vcc, exec
	s_cmp_lg_u32 s32, 0
	s_cbranch_scc1 .Ldk_nn0
	s_mov_b32 exec_lo, 0xffff
	s_mov_b32 exec_hi, 0
	global_load_dwordx4 v[4:7], v143, s[40:41] nt
	s_mov_b64 exec, vcc
; #define LAS __attribute__((address_space(3)))
; DI void decode_pair(const Params& p, LAS float* L  , int pairidx, int wid, int lane) {
;     ...
;         if (e < 387) {
;             const int pi = e / 129, j = e - pi * 129, d = 1 << (2 * pi), idx = 2048 - j * d;
;             const float* kr = (idx == 2048) ? knew : ck + ((size_t)(b * 2048 + idx) * 16 + h) * 64;
;             float dot = 0.f;
; #pragma unroll
;             for (int dd = 0; dd < 64; dd += 4) { const f32x4 kv = __builtin_nontemporal_load((const f32x4*)(kr + dd)); const f32x4 qv = *(const LAS f32x4*)(qs + dd); dot += kv.x * qv.x + kv.y * qv.y + kv.z * qv.z + kv.w * qv.w; }
;             sc[i] = dot - slope * (float)(j * d);
.Ldk_nn0:
	s_cmp_lg_u32 s32, 1
	s_cbranch_scc1 .Ldk_nn1
	s_mov_b32 exec_lo, 0xffff
	s_mov_b32 exec_hi, 0
	global_load_dwordx4 v[36:39], v143, s[40:41] nt
	s_mov_b64 exec, vcc
.Ldk_nn1:
	s_cmp_lg_u32 s32, 2
	s_cbranch_scc1 .Ldk_nn2
	s_mov_b32 exec_lo, 0xffff
	s_mov_b32 exec_hi, 0
	global_load_dwordx4 v[72:75], v143, s[40:41] nt
	s_mov_b64 exec, vcc
.Ldk_nn2:
	s_waitcnt vmcnt(0) lgkmcnt(0)
	v_mul_f32_e32 v4, v4, v220
	v_fmac_f32_e32 v4, v5, v221
	v_fmac_f32_e32 v4, v6, v222
	v_fmac_f32_e32 v4, v7, v223
	v_mul_f32_e32 v8, v8, v220
	v_fmac_f32_e32 v8, v9, v221
	v_fmac_f32_e32 v8, v10, v222
	v_fmac_f32_e32 v8, v11, v223
	v_mul_f32_e32 v12, v12, v220
	v_fmac_f32_e32 v12, v13, v221
	v_fmac_f32_e32 v12, v14, v222
	v_fmac_f32_e32 v12, v15, v223
	v_mul_f32_e32 v16, v16, v220
	v_fmac_f32_e32 v16, v17, v221
	v_fmac_f32_e32 v16, v18, v222
	v_fmac_f32_e32 v16, v19, v223
	v_mul_f32_e32 v20, v20, v220
	v_fmac_f32_e32 v20, v21, v221
	v_fmac_f32_e32 v20, v22, v222
	v_fmac_f32_e32 v20, v23, v223
	v_mul_f32_e32 v24, v24, v220
	v_fmac_f32_e32 v24, v25, v221
	v_fmac_f32_e32 v24, v26, v222
	v_fmac_f32_e32 v24, v27, v223
	v_mul_f32_e32 v28, v28, v220
	v_fmac_f32_e32 v28, v29, v221
	v_fmac_f32_e32 v28, v30, v222
	v_fmac_f32_e32 v28, v31, v223
	v_mul_f32_e32 v32, v32, v220
	v_fmac_f32_e32 v32, v33, v221
	v_fmac_f32_e32 v32, v34, v222
	v_fmac_f32_e32 v32, v35, v223
	v_mul_f32_e32 v36, v36, v220
	v_fmac_f32_e32 v36, v37, v221
	v_fmac_f32_e32 v36, v38, v222
	v_fmac_f32_e32 v36, v39, v223
	v_mul_f32_e32 v40, v40, v220
	v_fmac_f32_e32 v40, v41, v221
	v_fmac_f32_e32 v40, v42, v222
	v_fmac_f32_e32 v40, v43, v223
	v_mul_f32_e32 v44, v44, v220
	v_fmac_f32_e32 v44, v45, v221
	v_fmac_f32_e32 v44, v46, v222
	v_fmac_f32_e32 v44, v47, v223
	v_mul_f32_e32 v48, v48, v220
	v_fmac_f32_e32 v48, v49, v221
	v_fmac_f32_e32 v48, v50, v222
	v_fmac_f32_e32 v48, v51, v223
	v_mul_f32_e32 v52, v52, v220
	v_fmac_f32_e32 v52, v53, v221
	v_fmac_f32_e32 v52, v54, v222
	v_fmac_f32_e32 v52, v55, v223
	v_mul_f32_e32 v60, v60, v220
	v_fmac_f32_e32 v60, v61, v221
	v_fmac_f32_e32 v60, v62, v222
	v_fmac_f32_e32 v60, v63, v223
	v_mul_f32_e32 v64, v64, v220
	v_fmac_f32_e32 v64, v65, v221
	v_fmac_f32_e32 v64, v66, v222
	v_fmac_f32_e32 v64, v67, v223
	v_mul_f32_e32 v68, v68, v220
	v_fmac_f32_e32 v68, v69, v221
	v_fmac_f32_e32 v68, v70, v222
	v_fmac_f32_e32 v68, v71, v223
	v_mul_f32_e32 v72, v72, v220
	v_fmac_f32_e32 v72, v73, v221
	v_fmac_f32_e32 v72, v74, v222
	v_fmac_f32_e32 v72, v75, v223
	v_mul_f32_e32 v76, v76, v220
	v_fmac_f32_e32 v76, v77, v221
	v_fmac_f32_e32 v76, v78, v222
	v_fmac_f32_e32 v76, v79, v223
	v_mul_f32_e32 v80, v80, v220
	v_fmac_f32_e32 v80, v81, v221
	v_fmac_f32_e32 v80, v82, v222
	v_fmac_f32_e32 v80, v83, v223
	v_mul_f32_e32 v84, v84, v220
	v_fmac_f32_e32 v84, v85, v221
	v_fmac_f32_e32 v84, v86, v222
	v_fmac_f32_e32 v84, v87, v223
	v_mul_f32_e32 v88, v88, v220
	v_fmac_f32_e32 v88, v89, v221
	v_fmac_f32_e32 v88, v90, v222
	v_fmac_f32_e32 v88, v91, v223
	v_mul_f32_e32 v92, v92, v220
	v_fmac_f32_e32 v92, v93, v221
	v_fmac_f32_e32 v92, v94, v222
	v_fmac_f32_e32 v92, v95, v223
	v_mul_f32_e32 v96, v96, v220
	v_fmac_f32_e32 v96, v97, v221
	v_fmac_f32_e32 v96, v98, v222
	v_fmac_f32_e32 v96, v99, v223
	v_mul_f32_e32 v100, v100, v220
	v_fmac_f32_e32 v100, v101, v221
	v_fmac_f32_e32 v100, v102, v222
	v_fmac_f32_e32 v100, v103, v223
	v_mul_f32_e32 v104, v104, v220
	v_fmac_f32_e32 v104, v105, v221
	v_fmac_f32_e32 v104, v106, v222
	v_fmac_f32_e32 v104, v107, v223
	v_add_f32_dpp v5, v4, v4 quad_perm:[1,0,3,2] row_mask:0xf bank_mask:0xf
	v_add_f32_dpp v9, v8, v8 quad_perm:[1,0,3,2] row_mask:0xf bank_mask:0xf
	v_add_f32_dpp v13, v12, v12 quad_perm:[1,0,3,2] row_mask:0xf bank_mask:0xf
	v_add_f32_dpp v17, v16, v16 quad_perm:[1,0,3,2] row_mask:0xf bank_mask:0xf
	v_add_f32_dpp v21, v20, v20 quad_perm:[1,0,3,2] row_mask:0xf bank_mask:0xf
	v_add_f32_dpp v25, v24, v24 quad_perm:[1,0,3,2] row_mask:0xf bank_mask:0xf
	v_add_f32_dpp v29, v28, v28 quad_perm:[1,0,3,2] row_mask:0xf bank_mask:0xf
	v_add_f32_dpp v33, v32, v32 quad_perm:[1,0,3,2] row_mask:0xf bank_mask:0xf
	v_add_f32_dpp v37, v36, v36 quad_perm:[1,0,3,2] row_mask:0xf bank_mask:0xf
	v_add_f32_dpp v41, v40, v40 quad_perm:[1,0,3,2] row_mask:0xf bank_mask:0xf
	v_add_f32_dpp v45, v44, v44 quad_perm:[1,0,3,2] row_mask:0xf bank_mask:0xf
	v_add_f32_dpp v49, v48, v48 quad_perm:[1,0,3,2] row_mask:0xf bank_mask:0xf
	v_add_f32_dpp v53, v52, v52 quad_perm:[1,0,3,2] row_mask:0xf bank_mask:0xf
	v_add_f32_dpp v61, v60, v60 quad_perm:[1,0,3,2] row_mask:0xf bank_mask:0xf
	v_add_f32_dpp v65, v64, v64 quad_perm:[1,0,3,2] row_mask:0xf bank_mask:0xf
	v_add_f32_dpp v69, v68, v68 quad_perm:[1,0,3,2] row_mask:0xf bank_mask:0xf
	v_add_f32_dpp v73, v72, v72 quad_perm:[1,0,3,2] row_mask:0xf bank_mask:0xf
	v_add_f32_dpp v77, v76, v76 quad_perm:[1,0,3,2] row_mask:0xf bank_mask:0xf
	v_add_f32_dpp v81, v80, v80 quad_perm:[1,0,3,2] row_mask:0xf bank_mask:0xf
	v_add_f32_dpp v85, v84, v84 quad_perm:[1,0,3,2] row_mask:0xf bank_mask:0xf
	v_add_f32_dpp v89, v88, v88 quad_perm:[1,0,3,2] row_mask:0xf bank_mask:0xf
	v_add_f32_dpp v93, v92, v92 quad_perm:[1,0,3,2] row_mask:0xf bank_mask:0xf
	v_add_f32_dpp v97, v96, v96 quad_perm:[1,0,3,2] row_mask:0xf bank_mask:0xf
	v_add_f32_dpp v101, v100, v100 quad_perm:[1,0,3,2] row_mask:0xf bank_mask:0xf
	v_add_f32_dpp v105, v104, v104 quad_perm:[1,0,3,2] row_mask:0xf bank_mask:0xf
	v_add_f32_dpp v4, v5, v5 quad_perm:[2,3,0,1] row_mask:0xf bank_mask:0xf
	v_add_f32_dpp v8, v9, v9 quad_perm:[2,3,0,1] row_mask:0xf bank_mask:0xf
	v_add_f32_dpp v12, v13, v13 quad_perm:[2,3,0,1] row_mask:0xf bank_mask:0xf
	v_add_f32_dpp v16, v17, v17 quad_perm:[2,3,0,1] row_mask:0xf bank_mask:0xf
; #define LAS __attribute__((address_space(3)))
; DI void decode_pair(const Params& p, LAS float* L  , int pairidx, int wid, int lane) {
;     ...
;     for (int i = 0; i < 2; ++i) {
;         const int e = kq + 4 * (lane + 64 * i);
;         sc[i] = -INFINITY;
;         if (e < 387) {
;             const int pi = e / 129, j = e - pi * 129, d = 1 << (2 * pi), idx = 2048 - j * d;
;             const float* kr = (idx == 2048) ? knew : ck + ((size_t)(b * 2048 + idx) * 16 + h) * 64;
;             float dot = 0.f;
; #pragma unroll
;             for (int dd = 0; dd < 64; dd += 4) { const f32x4 kv = __builtin_nontemporal_load((const f32x4*)(kr + dd)); const f32x4 qv = *(const LAS f32x4*)(qs + dd); dot += kv.x * qv.x + kv.y * qv.y + kv.z * qv.z + kv.w * qv.w; }
;             sc[i] = dot - slope * (float)(j * d);
;         }
	v_add_f32_dpp v20, v21, v21 quad_perm:[2,3,0,1] row_mask:0xf bank_mask:0xf
	v_add_f32_dpp v24, v25, v25 quad_perm:[2,3,0,1] row_mask:0xf bank_mask:0xf
	v_add_f32_dpp v28, v29, v29 quad_perm:[2,3,0,1] row_mask:0xf bank_mask:0xf
	v_add_f32_dpp v32, v33, v33 quad_perm:[2,3,0,1] row_mask:0xf bank_mask:0xf
	v_add_f32_dpp v36, v37, v37 quad_perm:[2,3,0,1] row_mask:0xf bank_mask:0xf
	v_add_f32_dpp v40, v41, v41 quad_perm:[2,3,0,1] row_mask:0xf bank_mask:0xf
	v_add_f32_dpp v44, v45, v45 quad_perm:[2,3,0,1] row_mask:0xf bank_mask:0xf
	v_add_f32_dpp v48, v49, v49 quad_perm:[2,3,0,1] row_mask:0xf bank_mask:0xf
	v_add_f32_dpp v52, v53, v53 quad_perm:[2,3,0,1] row_mask:0xf bank_mask:0xf
	v_add_f32_dpp v60, v61, v61 quad_perm:[2,3,0,1] row_mask:0xf bank_mask:0xf
	v_add_f32_dpp v64, v65, v65 quad_perm:[2,3,0,1] row_mask:0xf bank_mask:0xf
	v_add_f32_dpp v68, v69, v69 quad_perm:[2,3,0,1] row_mask:0xf bank_mask:0xf
	v_add_f32_dpp v72, v73, v73 quad_perm:[2,3,0,1] row_mask:0xf bank_mask:0xf
	v_add_f32_dpp v76, v77, v77 quad_perm:[2,3,0,1] row_mask:0xf bank_mask:0xf
	v_add_f32_dpp v80, v81, v81 quad_perm:[2,3,0,1] row_mask:0xf bank_mask:0xf
	v_add_f32_dpp v84, v85, v85 quad_perm:[2,3,0,1] row_mask:0xf bank_mask:0xf
	v_add_f32_dpp v88, v89, v89 quad_perm:[2,3,0,1] row_mask:0xf bank_mask:0xf
	v_add_f32_dpp v92, v93, v93 quad_perm:[2,3,0,1] row_mask:0xf bank_mask:0xf
	v_add_f32_dpp v96, v97, v97 quad_perm:[2,3,0,1] row_mask:0xf bank_mask:0xf
	v_add_f32_dpp v100, v101, v101 quad_perm:[2,3,0,1] row_mask:0xf bank_mask:0xf
	v_add_f32_dpp v104, v105, v105 quad_perm:[2,3,0,1] row_mask:0xf bank_mask:0xf
	v_add_f32_dpp v5, v4, v4 row_half_mirror row_mask:0xf bank_mask:0xf
	v_add_f32_dpp v9, v8, v8 row_half_mirror row_mask:0xf bank_mask:0xf
	v_add_f32_dpp v13, v12, v12 row_half_mirror row_mask:0xf bank_mask:0xf
	v_add_f32_dpp v17, v16, v16 row_half_mirror row_mask:0xf bank_mask:0xf
	v_add_f32_dpp v21, v20, v20 row_half_mirror row_mask:0xf bank_mask:0xf
	v_add_f32_dpp v25, v24, v24 row_half_mirror row_mask:0xf bank_mask:0xf
	v_add_f32_dpp v29, v28, v28 row_half_mirror row_mask:0xf bank_mask:0xf
	v_add_f32_dpp v33, v32, v32 row_half_mirror row_mask:0xf bank_mask:0xf
	v_add_f32_dpp v37, v36, v36 row_half_mirror row_mask:0xf bank_mask:0xf
	v_add_f32_dpp v41, v40, v40 row_half_mirror row_mask:0xf bank_mask:0xf
	v_add_f32_dpp v45, v44, v44 row_half_mirror row_mask:0xf bank_mask:0xf
	v_add_f32_dpp v49, v48, v48 row_half_mirror row_mask:0xf bank_mask:0xf
	v_add_f32_dpp v53, v52, v52 row_half_mirror row_mask:0xf bank_mask:0xf
	v_add_f32_dpp v61, v60, v60 row_half_mirror row_mask:0xf bank_mask:0xf
	v_add_f32_dpp v65, v64, v64 row_half_mirror row_mask:0xf bank_mask:0xf
	v_add_f32_dpp v69, v68, v68 row_half_mirror row_mask:0xf bank_mask:0xf
	v_add_f32_dpp v73, v72, v72 row_half_mirror row_mask:0xf bank_mask:0xf
	v_add_f32_dpp v77, v76, v76 row_half_mirror row_mask:0xf bank_mask:0xf
	v_add_f32_dpp v81, v80, v80 row_half_mirror row_mask:0xf bank_mask:0xf
	v_add_f32_dpp v85, v84, v84 row_half_mirror row_mask:0xf bank_mask:0xf
	v_add_f32_dpp v89, v88, v88 row_half_mirror row_mask:0xf bank_mask:0xf
	v_add_f32_dpp v93, v92, v92 row_half_mirror row_mask:0xf bank_mask:0xf
	v_add_f32_dpp v97, v96, v96 row_half_mirror row_mask:0xf bank_mask:0xf
	v_add_f32_dpp v101, v100, v100 row_half_mirror row_mask:0xf bank_mask:0xf
	v_add_f32_dpp v105, v104, v104 row_half_mirror row_mask:0xf bank_mask:0xf
	v_add_f32_dpp v4, v5, v5 row_mirror row_mask:0xf bank_mask:0xf
	v_add_f32_dpp v8, v9, v9 row_mirror row_mask:0xf bank_mask:0xf
	v_add_f32_dpp v12, v13, v13 row_mirror row_mask:0xf bank_mask:0xf
	v_add_f32_dpp v16, v17, v17 row_mirror row_mask:0xf bank_mask:0xf
	v_add_f32_dpp v20, v21, v21 row_mirror row_mask:0xf bank_mask:0xf
	v_add_f32_dpp v24, v25, v25 row_mirror row_mask:0xf bank_mask:0xf
	v_add_f32_dpp v28, v29, v29 row_mirror row_mask:0xf bank_mask:0xf
	v_add_f32_dpp v32, v33, v33 row_mirror row_mask:0xf bank_mask:0xf
	v_add_f32_dpp v36, v37, v37 row_mirror row_mask:0xf bank_mask:0xf
	v_add_f32_dpp v40, v41, v41 row_mirror row_mask:0xf bank_mask:0xf
	v_add_f32_dpp v44, v45, v45 row_mirror row_mask:0xf bank_mask:0xf
	v_add_f32_dpp v48, v49, v49 row_mirror row_mask:0xf bank_mask:0xf
	v_add_f32_dpp v52, v53, v53 row_mirror row_mask:0xf bank_mask:0xf
	v_add_f32_dpp v60, v61, v61 row_mirror row_mask:0xf bank_mask:0xf
	v_add_f32_dpp v64, v65, v65 row_mirror row_mask:0xf bank_mask:0xf
	v_add_f32_dpp v68, v69, v69 row_mirror row_mask:0xf bank_mask:0xf
	v_add_f32_dpp v72, v73, v73 row_mirror row_mask:0xf bank_mask:0xf
	v_add_f32_dpp v76, v77, v77 row_mirror row_mask:0xf bank_mask:0xf
	v_add_f32_dpp v80, v81, v81 row_mirror row_mask:0xf bank_mask:0xf
	v_add_f32_dpp v84, v85, v85 row_mirror row_mask:0xf bank_mask:0xf
	v_add_f32_dpp v88, v89, v89 row_mirror row_mask:0xf bank_mask:0xf
	v_add_f32_dpp v92, v93, v93 row_mirror row_mask:0xf bank_mask:0xf
	v_add_f32_dpp v96, v97, v97 row_mirror row_mask:0xf bank_mask:0xf
	v_add_f32_dpp v100, v101, v101 row_mirror row_mask:0xf bank_mask:0xf
	v_add_f32_dpp v104, v105, v105 row_mirror row_mask:0xf bank_mask:0xf
	v_sub_f32_e32 v4, v4, v228
	v_sub_f32_e32 v8, v8, v229
	v_sub_f32_e32 v12, v12, v230
	v_sub_f32_e32 v16, v16, v231
	v_sub_f32_e32 v20, v20, v232
	v_sub_f32_e32 v24, v24, v233
	v_sub_f32_e32 v28, v28, v234
	v_sub_f32_e32 v32, v32, v235
	v_sub_f32_e32 v36, v36, v236
	v_sub_f32_e32 v40, v40, v237
	v_sub_f32_e32 v44, v44, v238
	v_sub_f32_e32 v48, v48, v239
	v_sub_f32_e32 v52, v52, v240
	v_sub_f32_e32 v60, v60, v241
	v_sub_f32_e32 v64, v64, v242
	v_sub_f32_e32 v68, v68, v124
	v_sub_f32_e32 v72, v72, v125
	v_sub_f32_e32 v76, v76, v188
	v_sub_f32_e32 v80, v80, v190
	v_sub_f32_e32 v84, v84, v192
	v_sub_f32_e32 v88, v88, v194
	v_sub_f32_e32 v92, v92, v196
	v_sub_f32_e32 v96, v96, v198
	v_sub_f32_e32 v100, v100, v200
	v_sub_f32_e32 v104, v104, v202
	s_mov_b32 exec_lo, 0x10001
	s_mov_b32 exec_hi, 0x10001
	ds_write_b32 v184, v4
	ds_write_b32 v184, v8 offset:16
	ds_write_b32 v184, v12 offset:32
	ds_write_b32 v184, v16 offset:48
	ds_write_b32 v184, v20 offset:64
	ds_write_b32 v184, v24 offset:80
	ds_write_b32 v184, v28 offset:96
	ds_write_b32 v184, v32 offset:112
	ds_write_b32 v184, v36 offset:128
	ds_write_b32 v184, v40 offset:144
	ds_write_b32 v184, v44 offset:160
	ds_write_b32 v184, v48 offset:176
	ds_write_b32 v184, v52 offset:192
	ds_write_b32 v184, v60 offset:208
	ds_write_b32 v184, v64 offset:224
	ds_write_b32 v184, v68 offset:240
	ds_write_b32 v184, v72 offset:256
	ds_write_b32 v184, v76 offset:272
	ds_write_b32 v184, v80 offset:288
	ds_write_b32 v184, v84 offset:304
	ds_write_b32 v184, v88 offset:320
	ds_write_b32 v184, v92 offset:336
	ds_write_b32 v184, v96 offset:352
	ds_write_b32 v184, v100 offset:368
	ds_write_b32 v184, v104 offset:384
	s_mov_b64 exec, vcc
	s_waitcnt lgkmcnt(0)
; DI void decode_pair(const Params& p, LAS float* L  , int pairidx, int wid, int lane) {
;     ...
;         mx = fmaxf(mx, sc[i]);
;     }
;     mx = wave_max(mx);
;     float ls = 0.f;
; #pragma unroll
;     for (int i = 0; i < 2; ++i) { const float pe = __expf(sc[i] - mx); ls += pe; pb[lane + 64 * i] = pe; }
;     ls = wave_sum(ls);
;     asm volatile("s_waitcnt lgkmcnt(0)" ::: "memory");
;     const int g = lane >> 4, dq = (lane & 15) * 4;
;     f32x4 acc = (f32x4){0.f, 0.f, 0.f, 0.f};
; #pragma unroll 5
;     for (int n = g; n < 97; n += 4) {
;         const int e = kq + 4 * n;
;         if (e < 387) {
;             const int pi = e / 129, j = e - pi * 129, d = 1 << (2 * pi), idx = 2048 - j * d;
;             const float* vr = (idx == 2048) ? vnew : cv + ((size_t)(b * 2048 + idx) * 16 + h) * 64;
;             acc += __builtin_nontemporal_load((const f32x4*)(vr + dq)) * pb[n];
;         }
;     }
	ds_read_b32 v2, v186
	ds_read_b32 v56, v186 offset:256
	v_add_u32_e32 v126, 64, v168
	v_cmp_le_u32_e32 vcc, v126, v176
	v_mov_b32_e32 v127, 0xff800000
	s_waitcnt lgkmcnt(0)
	v_cndmask_b32_e32 v56, v127, v56, vcc
	s_mov_b64 vcc, s[96:97]
	v_max3_f32 v0, v2, s54, v56
	v_cndmask_b32_e32 v3, v168, v3, vcc
	v_lshlrev_b32_e32 v3, 2, v3
	ds_bpermute_b32 v4, v3, v0
	s_waitcnt lgkmcnt(0)
	v_max_f32_e32 v4, v4, v4
	v_max_f32_e32 v0, v0, v4
	v_xor_b32_e32 v4, 2, v168
	v_cmp_lt_i32_e32 vcc, v4, v1
	s_nop 1
	v_cndmask_b32_e32 v4, v168, v4, vcc
	v_lshlrev_b32_e32 v4, 2, v4
	ds_bpermute_b32 v5, v4, v0
	s_waitcnt lgkmcnt(0)
	v_max_f32_e32 v5, v5, v5
	v_max_f32_e32 v0, v0, v5
	v_xor_b32_e32 v5, 4, v168
	v_cmp_lt_i32_e32 vcc, v5, v1
	s_nop 1
	v_cndmask_b32_e32 v5, v168, v5, vcc
	v_lshlrev_b32_e32 v5, 2, v5
	ds_bpermute_b32 v6, v5, v0
	s_waitcnt lgkmcnt(0)
	v_max_f32_e32 v6, v6, v6
	v_max_f32_e32 v0, v0, v6
	v_xor_b32_e32 v6, 8, v168
	v_cmp_lt_i32_e32 vcc, v6, v1
	s_nop 1
	v_cndmask_b32_e32 v6, v168, v6, vcc
	v_lshlrev_b32_e32 v6, 2, v6
	ds_bpermute_b32 v7, v6, v0
	s_waitcnt lgkmcnt(0)
	v_max_f32_e32 v7, v7, v7
	v_max_f32_e32 v0, v0, v7
	v_xor_b32_e32 v7, 16, v168
	v_cmp_lt_i32_e32 vcc, v7, v1
	s_nop 1
	v_cndmask_b32_e32 v7, v168, v7, vcc
	v_lshlrev_b32_e32 v12, 2, v7
	ds_bpermute_b32 v7, v12, v0
	s_waitcnt lgkmcnt(0)
	v_max_f32_e32 v7, v7, v7
	v_max_f32_e32 v0, v0, v7
	v_xor_b32_e32 v7, 32, v168
	v_cmp_lt_i32_e32 vcc, v7, v1
	s_nop 1
	v_cndmask_b32_e32 v1, v168, v7, vcc
	v_lshlrev_b32_e32 v1, 2, v1
	ds_bpermute_b32 v7, v1, v0
	s_waitcnt lgkmcnt(0)
	v_max_f32_e32 v7, v7, v7
	v_max_f32_e32 v0, v0, v7
	v_sub_f32_e32 v2, v2, v0
	v_mul_f32_e32 v2, 0x3fb8aa3b, v2
	v_sub_f32_e32 v7, v56, v0
	v_exp_f32_e32 v2, v2
	v_mul_f32_e32 v7, 0x3fb8aa3b, v7
	v_exp_f32_e32 v7, v7
	v_add_f32_e32 v8, 0, v2
	v_add_f32_e32 v8, v7, v8
	ds_bpermute_b32 v3, v3, v8
	ds_write2st64_b32 v148, v2, v7 offset0:1 offset1:2
	s_waitcnt lgkmcnt(0)
	v_mov_b32_e32 v2, v131
	s_waitcnt lgkmcnt(1)
	v_add_f32_e32 v3, v8, v3
	ds_bpermute_b32 v4, v4, v3
	v_mov_b32_e32 v8, v159
	s_waitcnt lgkmcnt(0)
	v_add_f32_e32 v3, v3, v4
	ds_bpermute_b32 v4, v5, v3
	v_mov_b32_e32 v5, v131
	s_waitcnt lgkmcnt(0)
	v_add_f32_e32 v3, v3, v4
	ds_bpermute_b32 v4, v6, v3
	v_lshl_add_u64 v[6:7], v[140:141], 2, s[42:43]
	s_waitcnt lgkmcnt(0)
	v_add_f32_e32 v3, v3, v4
	ds_bpermute_b32 v4, v12, v3
	s_waitcnt lgkmcnt(0)
	v_add_f32_e32 v10, v3, v4
	ds_bpermute_b32 v11, v1, v10
	v_mov_b32_e32 v4, v131
	v_mov_b32_e32 v3, v131
	v_ashrrev_i32_e32 v137, 31, v136
	v_lshlrev_b32_e32 v14, 2, v128
	v_mov_b32_e32 v15, v131
	v_mov_b32_e32 v2, v131
	v_mov_b32_e32 v5, v131
	v_mov_b32_e32 v16, v158
	v_mul_u32_u24_e32 v17, 0x3f81, v16
	v_lshrrev_b32_e32 v17, 21, v17
	v_mul_i32_i24_e32 v18, 0xffffff7f, v17
	v_add_u32_e32 v18, v18, v16
	v_cmp_eq_u32_e32 vcc, 0, v18
	v_lshlrev_b32_e32 v17, 1, v17
	v_lshlrev_b32_e32 v17, v17, v18
	v_sub_u32_e32 v20, v169, v17
	v_ashrrev_i32_e32 v21, 31, v20
	v_lshlrev_b64 v[20:21], 12, v[20:21]
	v_lshl_add_u64 v[20:21], s[80:81], 0, v[20:21]
	v_cndmask_b32_e32 v21, v21, v7, vcc
	v_cndmask_b32_e32 v20, v20, v6, vcc
	v_lshl_add_u64 v[20:21], v[20:21], 0, v[130:131]
	v_lshl_add_u64 v[20:21], v[20:21], 0, v[14:15]
	global_load_dwordx4 v[24:27], v[20:21], off nt
	ds_read_b32 v170, v156 offset:0
	v_add_u32_e32 v16, 16, v158
	v_mul_u32_u24_e32 v17, 0x3f81, v16
	v_lshrrev_b32_e32 v17, 21, v17
	v_mul_i32_i24_e32 v18, 0xffffff7f, v17
	v_add_u32_e32 v18, v18, v16
	v_cmp_eq_u32_e32 vcc, 0, v18
	v_lshlrev_b32_e32 v17, 1, v17
	v_lshlrev_b32_e32 v17, v17, v18
	v_sub_u32_e32 v20, v169, v17
	v_ashrrev_i32_e32 v21, 31, v20
	v_lshlrev_b64 v[20:21], 12, v[20:21]
	v_lshl_add_u64 v[20:21], s[80:81], 0, v[20:21]
	v_cndmask_b32_e32 v21, v21, v7, vcc
	v_cndmask_b32_e32 v20, v20, v6, vcc
	v_lshl_add_u64 v[20:21], v[20:21], 0, v[130:131]
	v_lshl_add_u64 v[20:21], v[20:21], 0, v[14:15]
	global_load_dwordx4 v[28:31], v[20:21], off nt
	ds_read_b32 v172, v156 offset:16
	v_add_u32_e32 v16, 32, v158
	v_mul_u32_u24_e32 v17, 0x3f81, v16
	v_lshrrev_b32_e32 v17, 21, v17
	v_mul_i32_i24_e32 v18, 0xffffff7f, v17
	v_add_u32_e32 v18, v18, v16
	v_cmp_eq_u32_e32 vcc, 0, v18
	v_lshlrev_b32_e32 v17, 1, v17
	v_lshlrev_b32_e32 v17, v17, v18
	v_sub_u32_e32 v20, v169, v17
	v_ashrrev_i32_e32 v21, 31, v20
	v_lshlrev_b64 v[20:21], 12, v[20:21]
	v_lshl_add_u64 v[20:21], s[80:81], 0, v[20:21]
	v_cndmask_b32_e32 v21, v21, v7, vcc
	v_cndmask_b32_e32 v20, v20, v6, vcc
	v_lshl_add_u64 v[20:21], v[20:21], 0, v[130:131]
	v_lshl_add_u64 v[20:21], v[20:21], 0, v[14:15]
	global_load_dwordx4 v[32:35], v[20:21], off nt
	ds_read_b32 v174, v156 offset:32
	v_add_u32_e32 v16, 48, v158
	v_mul_u32_u24_e32 v17, 0x3f81, v16
	v_lshrrev_b32_e32 v17, 21, v17
	v_mul_i32_i24_e32 v18, 0xffffff7f, v17
	v_add_u32_e32 v18, v18, v16
	v_cmp_eq_u32_e32 vcc, 0, v18
	v_lshlrev_b32_e32 v17, 1, v17
	v_lshlrev_b32_e32 v17, v17, v18
	v_sub_u32_e32 v20, v169, v17
	v_ashrrev_i32_e32 v21, 31, v20
	v_lshlrev_b64 v[20:21], 12, v[20:21]
	v_lshl_add_u64 v[20:21], s[80:81], 0, v[20:21]
	v_cndmask_b32_e32 v21, v21, v7, vcc
	v_cndmask_b32_e32 v20, v20, v6, vcc
	v_lshl_add_u64 v[20:21], v[20:21], 0, v[130:131]
	v_lshl_add_u64 v[20:21], v[20:21], 0, v[14:15]
	global_load_dwordx4 v[36:39], v[20:21], off nt
	ds_read_b32 v176, v156 offset:48
	v_add_u32_e32 v16, 64, v158
	v_mul_u32_u24_e32 v17, 0x3f81, v16
	v_lshrrev_b32_e32 v17, 21, v17
	v_mul_i32_i24_e32 v18, 0xffffff7f, v17
	v_add_u32_e32 v18, v18, v16
	v_cmp_eq_u32_e32 vcc, 0, v18
	v_lshlrev_b32_e32 v17, 1, v17
	v_lshlrev_b32_e32 v17, v17, v18
	v_sub_u32_e32 v20, v169, v17
	v_ashrrev_i32_e32 v21, 31, v20
	v_lshlrev_b64 v[20:21], 12, v[20:21]
; DI void decode_pair(const Params& p, LAS float* L  , int pairidx, int wid, int lane) {
;     ...
; #pragma unroll 5
;     for (int n = g; n < 97; n += 4) {
;         const int e = kq + 4 * n;
;         if (e < 387) {
;             const int pi = e / 129, j = e - pi * 129, d = 1 << (2 * pi), idx = 2048 - j * d;
;             const float* vr = (idx == 2048) ? vnew : cv + ((size_t)(b * 2048 + idx) * 16 + h) * 64;
;             acc += __builtin_nontemporal_load((const f32x4*)(vr + dq)) * pb[n];
;         }
;     }
	v_lshl_add_u64 v[20:21], s[80:81], 0, v[20:21]
	v_cndmask_b32_e32 v21, v21, v7, vcc
	v_cndmask_b32_e32 v20, v20, v6, vcc
	v_lshl_add_u64 v[20:21], v[20:21], 0, v[130:131]
	v_lshl_add_u64 v[20:21], v[20:21], 0, v[14:15]
	global_load_dwordx4 v[40:43], v[20:21], off nt
	ds_read_b32 v178, v156 offset:64
	v_add_u32_e32 v16, 80, v158
	v_mul_u32_u24_e32 v17, 0x3f81, v16
	v_lshrrev_b32_e32 v17, 21, v17
	v_mul_i32_i24_e32 v18, 0xffffff7f, v17
	v_add_u32_e32 v18, v18, v16
	v_cmp_eq_u32_e32 vcc, 0, v18
	v_lshlrev_b32_e32 v17, 1, v17
	v_lshlrev_b32_e32 v17, v17, v18
	v_sub_u32_e32 v20, v169, v17
	v_ashrrev_i32_e32 v21, 31, v20
	v_lshlrev_b64 v[20:21], 12, v[20:21]
	v_lshl_add_u64 v[20:21], s[80:81], 0, v[20:21]
	v_cndmask_b32_e32 v21, v21, v7, vcc
	v_cndmask_b32_e32 v20, v20, v6, vcc
	v_lshl_add_u64 v[20:21], v[20:21], 0, v[130:131]
	v_lshl_add_u64 v[20:21], v[20:21], 0, v[14:15]
	global_load_dwordx4 v[44:47], v[20:21], off nt
	ds_read_b32 v180, v156 offset:80
	v_add_u32_e32 v16, 96, v158
	v_mul_u32_u24_e32 v17, 0x3f81, v16
	v_lshrrev_b32_e32 v17, 21, v17
	v_mul_i32_i24_e32 v18, 0xffffff7f, v17
	v_add_u32_e32 v18, v18, v16
	v_cmp_eq_u32_e32 vcc, 0, v18
	v_lshlrev_b32_e32 v17, 1, v17
	v_lshlrev_b32_e32 v17, v17, v18
	v_sub_u32_e32 v20, v169, v17
	v_ashrrev_i32_e32 v21, 31, v20
	v_lshlrev_b64 v[20:21], 12, v[20:21]
	v_lshl_add_u64 v[20:21], s[80:81], 0, v[20:21]
	v_cndmask_b32_e32 v21, v21, v7, vcc
	v_cndmask_b32_e32 v20, v20, v6, vcc
	v_lshl_add_u64 v[20:21], v[20:21], 0, v[130:131]
	v_lshl_add_u64 v[20:21], v[20:21], 0, v[14:15]
	global_load_dwordx4 v[48:51], v[20:21], off nt
	ds_read_b32 v182, v156 offset:96
	v_add_u32_e32 v16, 112, v158
	v_mul_u32_u24_e32 v17, 0x3f81, v16
	v_lshrrev_b32_e32 v17, 21, v17
	v_mul_i32_i24_e32 v18, 0xffffff7f, v17
	v_add_u32_e32 v18, v18, v16
	v_cmp_eq_u32_e32 vcc, 0, v18
	v_lshlrev_b32_e32 v17, 1, v17
	v_lshlrev_b32_e32 v17, v17, v18
	v_sub_u32_e32 v20, v169, v17
	v_ashrrev_i32_e32 v21, 31, v20
	v_lshlrev_b64 v[20:21], 12, v[20:21]
	v_lshl_add_u64 v[20:21], s[80:81], 0, v[20:21]
	v_cndmask_b32_e32 v21, v21, v7, vcc
	v_cndmask_b32_e32 v20, v20, v6, vcc
	v_lshl_add_u64 v[20:21], v[20:21], 0, v[130:131]
	v_lshl_add_u64 v[20:21], v[20:21], 0, v[14:15]
	global_load_dwordx4 v[52:55], v[20:21], off nt
	ds_read_b32 v184, v156 offset:112
	v_add_u32_e32 v16, 128, v158
	v_mul_u32_u24_e32 v17, 0x3f81, v16
	v_lshrrev_b32_e32 v17, 21, v17
	v_mul_i32_i24_e32 v18, 0xffffff7f, v17
	v_add_u32_e32 v18, v18, v16
	v_cmp_eq_u32_e32 vcc, 0, v18
	v_lshlrev_b32_e32 v17, 1, v17
	v_lshlrev_b32_e32 v17, v17, v18
	v_sub_u32_e32 v20, v169, v17
	v_ashrrev_i32_e32 v21, 31, v20
	v_lshlrev_b64 v[20:21], 12, v[20:21]
	v_lshl_add_u64 v[20:21], s[80:81], 0, v[20:21]
	v_cndmask_b32_e32 v21, v21, v7, vcc
	v_cndmask_b32_e32 v20, v20, v6, vcc
	v_lshl_add_u64 v[20:21], v[20:21], 0, v[130:131]
	v_lshl_add_u64 v[20:21], v[20:21], 0, v[14:15]
	global_load_dwordx4 v[56:59], v[20:21], off nt
	ds_read_b32 v186, v156 offset:128
	v_add_u32_e32 v16, 144, v158
	v_mul_u32_u24_e32 v17, 0x3f81, v16
	v_lshrrev_b32_e32 v17, 21, v17
	v_mul_i32_i24_e32 v18, 0xffffff7f, v17
	v_add_u32_e32 v18, v18, v16
	v_cmp_eq_u32_e32 vcc, 0, v18
	v_lshlrev_b32_e32 v17, 1, v17
	v_lshlrev_b32_e32 v17, v17, v18
	v_sub_u32_e32 v20, v169, v17
	v_ashrrev_i32_e32 v21, 31, v20
	v_lshlrev_b64 v[20:21], 12, v[20:21]
	v_lshl_add_u64 v[20:21], s[80:81], 0, v[20:21]
	v_cndmask_b32_e32 v21, v21, v7, vcc
	v_cndmask_b32_e32 v20, v20, v6, vcc
	v_lshl_add_u64 v[20:21], v[20:21], 0, v[130:131]
	v_lshl_add_u64 v[20:21], v[20:21], 0, v[14:15]
	global_load_dwordx4 v[60:63], v[20:21], off nt
	ds_read_b32 v188, v156 offset:144
	v_add_u32_e32 v16, 160, v158
	v_mul_u32_u24_e32 v17, 0x3f81, v16
	v_lshrrev_b32_e32 v17, 21, v17
	v_mul_i32_i24_e32 v18, 0xffffff7f, v17
	v_add_u32_e32 v18, v18, v16
	v_cmp_eq_u32_e32 vcc, 0, v18
	v_lshlrev_b32_e32 v17, 1, v17
	v_lshlrev_b32_e32 v17, v17, v18
	v_sub_u32_e32 v20, v169, v17
	v_ashrrev_i32_e32 v21, 31, v20
	v_lshlrev_b64 v[20:21], 12, v[20:21]
	v_lshl_add_u64 v[20:21], s[80:81], 0, v[20:21]
	v_cndmask_b32_e32 v21, v21, v7, vcc
	v_cndmask_b32_e32 v20, v20, v6, vcc
	v_lshl_add_u64 v[20:21], v[20:21], 0, v[130:131]
	v_lshl_add_u64 v[20:21], v[20:21], 0, v[14:15]
	global_load_dwordx4 v[64:67], v[20:21], off nt
	ds_read_b32 v190, v156 offset:160
	v_add_u32_e32 v16, 176, v158
	v_mul_u32_u24_e32 v17, 0x3f81, v16
	v_lshrrev_b32_e32 v17, 21, v17
	v_mul_i32_i24_e32 v18, 0xffffff7f, v17
	v_add_u32_e32 v18, v18, v16
	v_cmp_eq_u32_e32 vcc, 0, v18
	v_lshlrev_b32_e32 v17, 1, v17
	v_lshlrev_b32_e32 v17, v17, v18
	v_sub_u32_e32 v20, v169, v17
	v_ashrrev_i32_e32 v21, 31, v20
	v_lshlrev_b64 v[20:21], 12, v[20:21]
	v_lshl_add_u64 v[20:21], s[80:81], 0, v[20:21]
	v_cndmask_b32_e32 v21, v21, v7, vcc
	v_cndmask_b32_e32 v20, v20, v6, vcc
	v_lshl_add_u64 v[20:21], v[20:21], 0, v[130:131]
	v_lshl_add_u64 v[20:21], v[20:21], 0, v[14:15]
	global_load_dwordx4 v[68:71], v[20:21], off nt
	ds_read_b32 v192, v156 offset:176
	v_add_u32_e32 v16, 192, v158
	v_mul_u32_u24_e32 v17, 0x3f81, v16
	v_lshrrev_b32_e32 v17, 21, v17
	v_mul_i32_i24_e32 v18, 0xffffff7f, v17
	v_add_u32_e32 v18, v18, v16
	v_cmp_eq_u32_e32 vcc, 0, v18
	v_lshlrev_b32_e32 v17, 1, v17
	v_lshlrev_b32_e32 v17, v17, v18
	v_sub_u32_e32 v20, v169, v17
	v_ashrrev_i32_e32 v21, 31, v20
	v_lshlrev_b64 v[20:21], 12, v[20:21]
	v_lshl_add_u64 v[20:21], s[80:81], 0, v[20:21]
	v_cndmask_b32_e32 v21, v21, v7, vcc
	v_cndmask_b32_e32 v20, v20, v6, vcc
	v_lshl_add_u64 v[20:21], v[20:21], 0, v[130:131]
	v_lshl_add_u64 v[20:21], v[20:21], 0, v[14:15]
	global_load_dwordx4 v[72:75], v[20:21], off nt
	ds_read_b32 v194, v156 offset:192
	v_add_u32_e32 v16, 208, v158
; DI void decode_pair(const Params& p, LAS float* L  , int pairidx, int wid, int lane) {
;     ...
; #pragma unroll 5
;     for (int n = g; n < 97; n += 4) {
;         const int e = kq + 4 * n;
;         if (e < 387) {
;             const int pi = e / 129, j = e - pi * 129, d = 1 << (2 * pi), idx = 2048 - j * d;
;             const float* vr = (idx == 2048) ? vnew : cv + ((size_t)(b * 2048 + idx) * 16 + h) * 64;
;             acc += __builtin_nontemporal_load((const f32x4*)(vr + dq)) * pb[n];
;         }
;     }
	v_mul_u32_u24_e32 v17, 0x3f81, v16
	v_lshrrev_b32_e32 v17, 21, v17
	v_mul_i32_i24_e32 v18, 0xffffff7f, v17
	v_add_u32_e32 v18, v18, v16
	v_cmp_eq_u32_e32 vcc, 0, v18
	v_lshlrev_b32_e32 v17, 1, v17
	v_lshlrev_b32_e32 v17, v17, v18
	v_sub_u32_e32 v20, v169, v17
	v_ashrrev_i32_e32 v21, 31, v20
	v_lshlrev_b64 v[20:21], 12, v[20:21]
	v_lshl_add_u64 v[20:21], s[80:81], 0, v[20:21]
	v_cndmask_b32_e32 v21, v21, v7, vcc
	v_cndmask_b32_e32 v20, v20, v6, vcc
	v_lshl_add_u64 v[20:21], v[20:21], 0, v[130:131]
	v_lshl_add_u64 v[20:21], v[20:21], 0, v[14:15]
	global_load_dwordx4 v[76:79], v[20:21], off nt
	ds_read_b32 v196, v156 offset:208
	v_add_u32_e32 v16, 224, v158
	v_mul_u32_u24_e32 v17, 0x3f81, v16
	v_lshrrev_b32_e32 v17, 21, v17
	v_mul_i32_i24_e32 v18, 0xffffff7f, v17
	v_add_u32_e32 v18, v18, v16
	v_cmp_eq_u32_e32 vcc, 0, v18
	v_lshlrev_b32_e32 v17, 1, v17
	v_lshlrev_b32_e32 v17, v17, v18
	v_sub_u32_e32 v20, v169, v17
	v_ashrrev_i32_e32 v21, 31, v20
	v_lshlrev_b64 v[20:21], 12, v[20:21]
	v_lshl_add_u64 v[20:21], s[80:81], 0, v[20:21]
	v_cndmask_b32_e32 v21, v21, v7, vcc
	v_cndmask_b32_e32 v20, v20, v6, vcc
	v_lshl_add_u64 v[20:21], v[20:21], 0, v[130:131]
	v_lshl_add_u64 v[20:21], v[20:21], 0, v[14:15]
	global_load_dwordx4 v[80:83], v[20:21], off nt
	ds_read_b32 v198, v156 offset:224
	v_add_u32_e32 v16, 240, v158
	v_mul_u32_u24_e32 v17, 0x3f81, v16
	v_lshrrev_b32_e32 v17, 21, v17
	v_mul_i32_i24_e32 v18, 0xffffff7f, v17
	v_add_u32_e32 v18, v18, v16
	v_cmp_eq_u32_e32 vcc, 0, v18
	v_lshlrev_b32_e32 v17, 1, v17
	v_lshlrev_b32_e32 v17, v17, v18
	v_sub_u32_e32 v20, v169, v17
	v_ashrrev_i32_e32 v21, 31, v20
	v_lshlrev_b64 v[20:21], 12, v[20:21]
	v_lshl_add_u64 v[20:21], s[80:81], 0, v[20:21]
	v_cndmask_b32_e32 v21, v21, v7, vcc
	v_cndmask_b32_e32 v20, v20, v6, vcc
	v_lshl_add_u64 v[20:21], v[20:21], 0, v[130:131]
	v_lshl_add_u64 v[20:21], v[20:21], 0, v[14:15]
	global_load_dwordx4 v[84:87], v[20:21], off nt
	ds_read_b32 v200, v156 offset:240
	v_add_u32_e32 v16, 256, v158
	v_mul_u32_u24_e32 v17, 0x3f81, v16
	v_lshrrev_b32_e32 v17, 21, v17
	v_mul_i32_i24_e32 v18, 0xffffff7f, v17
	v_add_u32_e32 v18, v18, v16
	v_cmp_eq_u32_e32 vcc, 0, v18
	v_lshlrev_b32_e32 v17, 1, v17
	v_lshlrev_b32_e32 v17, v17, v18
	v_sub_u32_e32 v20, v169, v17
	v_ashrrev_i32_e32 v21, 31, v20
	v_lshlrev_b64 v[20:21], 12, v[20:21]
	v_lshl_add_u64 v[20:21], s[80:81], 0, v[20:21]
	v_cndmask_b32_e32 v21, v21, v7, vcc
	v_cndmask_b32_e32 v20, v20, v6, vcc
	v_lshl_add_u64 v[20:21], v[20:21], 0, v[130:131]
	v_lshl_add_u64 v[20:21], v[20:21], 0, v[14:15]
	global_load_dwordx4 v[88:91], v[20:21], off nt
	ds_read_b32 v202, v156 offset:256
	v_add_u32_e32 v16, 272, v158
	v_mul_u32_u24_e32 v17, 0x3f81, v16
	v_lshrrev_b32_e32 v17, 21, v17
	v_mul_i32_i24_e32 v18, 0xffffff7f, v17
	v_add_u32_e32 v18, v18, v16
	v_cmp_eq_u32_e32 vcc, 0, v18
	v_lshlrev_b32_e32 v17, 1, v17
	v_lshlrev_b32_e32 v17, v17, v18
	v_sub_u32_e32 v20, v169, v17
	v_ashrrev_i32_e32 v21, 31, v20
	v_lshlrev_b64 v[20:21], 12, v[20:21]
	v_lshl_add_u64 v[20:21], s[80:81], 0, v[20:21]
	v_cndmask_b32_e32 v21, v21, v7, vcc
	v_cndmask_b32_e32 v20, v20, v6, vcc
	v_lshl_add_u64 v[20:21], v[20:21], 0, v[130:131]
	v_lshl_add_u64 v[20:21], v[20:21], 0, v[14:15]
	global_load_dwordx4 v[92:95], v[20:21], off nt
	ds_read_b32 v204, v156 offset:272
	v_add_u32_e32 v16, 288, v158
	v_mul_u32_u24_e32 v17, 0x3f81, v16
	v_lshrrev_b32_e32 v17, 21, v17
	v_mul_i32_i24_e32 v18, 0xffffff7f, v17
	v_add_u32_e32 v18, v18, v16
	v_cmp_eq_u32_e32 vcc, 0, v18
	v_lshlrev_b32_e32 v17, 1, v17
	v_lshlrev_b32_e32 v17, v17, v18
	v_sub_u32_e32 v20, v169, v17
	v_ashrrev_i32_e32 v21, 31, v20
	v_lshlrev_b64 v[20:21], 12, v[20:21]
	v_lshl_add_u64 v[20:21], s[80:81], 0, v[20:21]
	v_cndmask_b32_e32 v21, v21, v7, vcc
	v_cndmask_b32_e32 v20, v20, v6, vcc
	v_lshl_add_u64 v[20:21], v[20:21], 0, v[130:131]
	v_lshl_add_u64 v[20:21], v[20:21], 0, v[14:15]
	global_load_dwordx4 v[96:99], v[20:21], off nt
	ds_read_b32 v206, v156 offset:288
	v_add_u32_e32 v16, 304, v158
	v_mul_u32_u24_e32 v17, 0x3f81, v16
; DI void decode_pair(const Params& p, LAS float* L  , int pairidx, int wid, int lane) {
;     ...
; #pragma unroll 5
;     for (int n = g; n < 97; n += 4) {
;         const int e = kq + 4 * n;
;         if (e < 387) {
;             const int pi = e / 129, j = e - pi * 129, d = 1 << (2 * pi), idx = 2048 - j * d;
;             const float* vr = (idx == 2048) ? vnew : cv + ((size_t)(b * 2048 + idx) * 16 + h) * 64;
;             acc += __builtin_nontemporal_load((const f32x4*)(vr + dq)) * pb[n];
;         }
;     }
	v_lshrrev_b32_e32 v17, 21, v17
	v_mul_i32_i24_e32 v18, 0xffffff7f, v17
	v_add_u32_e32 v18, v18, v16
	v_cmp_eq_u32_e32 vcc, 0, v18
	v_lshlrev_b32_e32 v17, 1, v17
	v_lshlrev_b32_e32 v17, v17, v18
	v_sub_u32_e32 v20, v169, v17
	v_ashrrev_i32_e32 v21, 31, v20
	v_lshlrev_b64 v[20:21], 12, v[20:21]
	v_lshl_add_u64 v[20:21], s[80:81], 0, v[20:21]
	v_cndmask_b32_e32 v21, v21, v7, vcc
	v_cndmask_b32_e32 v20, v20, v6, vcc
	v_lshl_add_u64 v[20:21], v[20:21], 0, v[130:131]
	v_lshl_add_u64 v[20:21], v[20:21], 0, v[14:15]
	global_load_dwordx4 v[100:103], v[20:21], off nt
	ds_read_b32 v208, v156 offset:304
	v_add_u32_e32 v16, 320, v158
	v_mul_u32_u24_e32 v17, 0x3f81, v16
	v_lshrrev_b32_e32 v17, 21, v17
	v_mul_i32_i24_e32 v18, 0xffffff7f, v17
	v_add_u32_e32 v18, v18, v16
	v_cmp_eq_u32_e32 vcc, 0, v18
	v_lshlrev_b32_e32 v17, 1, v17
	v_lshlrev_b32_e32 v17, v17, v18
	v_sub_u32_e32 v20, v169, v17
	v_ashrrev_i32_e32 v21, 31, v20
	v_lshlrev_b64 v[20:21], 12, v[20:21]
	v_lshl_add_u64 v[20:21], s[80:81], 0, v[20:21]
	v_cndmask_b32_e32 v21, v21, v7, vcc
	v_cndmask_b32_e32 v20, v20, v6, vcc
	v_lshl_add_u64 v[20:21], v[20:21], 0, v[130:131]
	v_lshl_add_u64 v[20:21], v[20:21], 0, v[14:15]
	global_load_dwordx4 v[104:107], v[20:21], off nt
	ds_read_b32 v210, v156 offset:320
	v_add_u32_e32 v16, 336, v158
	v_mul_u32_u24_e32 v17, 0x3f81, v16
	v_lshrrev_b32_e32 v17, 21, v17
	v_mul_i32_i24_e32 v18, 0xffffff7f, v17
	v_add_u32_e32 v18, v18, v16
	v_cmp_eq_u32_e32 vcc, 0, v18
	v_lshlrev_b32_e32 v17, 1, v17
	v_lshlrev_b32_e32 v17, v17, v18
	v_sub_u32_e32 v20, v169, v17
	v_ashrrev_i32_e32 v21, 31, v20
	v_lshlrev_b64 v[20:21], 12, v[20:21]
	v_lshl_add_u64 v[20:21], s[80:81], 0, v[20:21]
	v_cndmask_b32_e32 v21, v21, v7, vcc
	v_cndmask_b32_e32 v20, v20, v6, vcc
	v_lshl_add_u64 v[20:21], v[20:21], 0, v[130:131]
	v_lshl_add_u64 v[20:21], v[20:21], 0, v[14:15]
	global_load_dwordx4 v[108:111], v[20:21], off nt
	ds_read_b32 v212, v156 offset:336
	v_add_u32_e32 v16, 352, v158
	v_mul_u32_u24_e32 v17, 0x3f81, v16
	v_lshrrev_b32_e32 v17, 21, v17
	v_mul_i32_i24_e32 v18, 0xffffff7f, v17
	v_add_u32_e32 v18, v18, v16
	v_cmp_eq_u32_e32 vcc, 0, v18
	v_lshlrev_b32_e32 v17, 1, v17
	v_lshlrev_b32_e32 v17, v17, v18
	v_sub_u32_e32 v20, v169, v17
	v_ashrrev_i32_e32 v21, 31, v20
	v_lshlrev_b64 v[20:21], 12, v[20:21]
	v_lshl_add_u64 v[20:21], s[80:81], 0, v[20:21]
	v_cndmask_b32_e32 v21, v21, v7, vcc
	v_cndmask_b32_e32 v20, v20, v6, vcc
	v_lshl_add_u64 v[20:21], v[20:21], 0, v[130:131]
	v_lshl_add_u64 v[20:21], v[20:21], 0, v[14:15]
	global_load_dwordx4 v[112:115], v[20:21], off nt
	ds_read_b32 v214, v156 offset:352
	v_add_u32_e32 v16, 368, v158
	v_mul_u32_u24_e32 v17, 0x3f81, v16
	v_lshrrev_b32_e32 v17, 21, v17
	v_mul_i32_i24_e32 v18, 0xffffff7f, v17
	v_add_u32_e32 v18, v18, v16
	v_cmp_eq_u32_e32 vcc, 0, v18
	v_lshlrev_b32_e32 v17, 1, v17
	v_lshlrev_b32_e32 v17, v17, v18
	v_sub_u32_e32 v20, v169, v17
	v_ashrrev_i32_e32 v21, 31, v20
	v_lshlrev_b64 v[20:21], 12, v[20:21]
	v_lshl_add_u64 v[20:21], s[80:81], 0, v[20:21]
	v_cndmask_b32_e32 v21, v21, v7, vcc
	v_cndmask_b32_e32 v20, v20, v6, vcc
	v_lshl_add_u64 v[20:21], v[20:21], 0, v[130:131]
	v_lshl_add_u64 v[20:21], v[20:21], 0, v[14:15]
	global_load_dwordx4 v[116:119], v[20:21], off nt
	ds_read_b32 v216, v156 offset:368
	v_cmp_gt_u32_e32 vcc, 3, v158
	s_and_saveexec_b64 s[18:19], vcc
	s_cbranch_execz .Ldv_skip_a
	v_add_u32_e32 v16, 384, v158
	v_mul_u32_u24_e32 v17, 0x3f81, v16
	v_lshrrev_b32_e32 v17, 21, v17
	v_mul_i32_i24_e32 v18, 0xffffff7f, v17
	v_add_u32_e32 v18, v18, v16
	v_cmp_eq_u32_e32 vcc, 0, v18
	v_lshlrev_b32_e32 v17, 1, v17
	v_lshlrev_b32_e32 v17, v17, v18
	v_sub_u32_e32 v20, v169, v17
	v_ashrrev_i32_e32 v21, 31, v20
	v_lshlrev_b64 v[20:21], 12, v[20:21]
	v_lshl_add_u64 v[20:21], s[80:81], 0, v[20:21]
	v_cndmask_b32_e32 v21, v21, v7, vcc
	v_cndmask_b32_e32 v20, v20, v6, vcc
	v_lshl_add_u64 v[20:21], v[20:21], 0, v[130:131]
	v_lshl_add_u64 v[20:21], v[20:21], 0, v[14:15]
	global_load_dwordx4 v[120:123], v[20:21], off nt
	ds_read_b32 v218, v156 offset:384
